# scan producer V-chunk staging remapped to coalesced 64B row segments; producer counted vmcnt waits; DPP row-norm reduce; attention q/gate prefetch one unit ahead + sink via SMEM
# speedup vs baseline: 1.2409x; 1.0055x over previous
.LBB0_288:
	s_add_i32 s0, s17, 31
	s_lshr_b32 s18, s0, 5
	s_add_i32 s0, s18, 3
	s_and_b32 s19, s0, 0x46
	s_cmp_eq_u32 s19, 0
	s_cbranch_scc1 .LBB0_283
	s_and_b32 s0, s16, 15
	s_add_i32 s20, s18, -1
	s_ashr_i32 s9, s8, 31
	s_cmp_eq_u32 s20, 0
	v_add_u32_e32 v56, s8, v176
	s_cselect_b32 s1, 0, 32
	s_waitcnt vmcnt(0)
	v_add_u32_e32 v20, s1, v56
	v_ashrrev_i32_e32 v21, 31, v20
	v_lshl_add_u32 v58, s0, 7, v55
	v_mov_b32_e32 v59, v2
	v_lshlrev_b64 v[20:21], 11, v[20:21]
	v_lshl_add_u64 v[20:21], v[20:21], 0, v[58:59]
	v_lshlrev_b64 v[22:23], 1, v[20:21]
	v_lshl_add_u64 v[24:25], s[72:73], 0, v[22:23]
	v_add_co_u32_e32 v26, vcc, s33, v24
	v_lshl_add_u64 v[22:23], s[64:65], 0, v[22:23]
	s_nop 0
	v_addc_co_u32_e32 v27, vcc, 0, v25, vcc
	v_add_co_u32_e32 v28, vcc, s33, v22
	v_lshl_add_u64 v[20:21], v[20:21], 2, s[74:75]
	s_nop 0
	v_addc_co_u32_e32 v29, vcc, 0, v23, vcc
	s_mov_b32 s3, 0xe000
	v_add_co_u32_e32 v30, vcc, s3, v20
	v_readlane_b32 s10, v251, 37
	s_nop 0
	v_addc_co_u32_e32 v31, vcc, 0, v21, vcc
	v_readlane_b32 s11, v251, 38
	v_add_co_u32_e32 v32, vcc, s63, v24
	v_lshrrev_b32_e32 v6, 2, v53
	v_lshl_add_u32 v6, s0, 8, v6
	v_mov_b64_e32 v[4:5], s[10:11]
	v_addc_co_u32_e32 v33, vcc, 0, v25, vcc
	v_mad_i64_i32 v[4:5], s[10:11], v6, s93, v[4:5]
	v_add_co_u32_e32 v34, vcc, s63, v22
	v_readlane_b32 s10, v253, 63
	s_nop 0
	v_addc_co_u32_e32 v35, vcc, 0, v23, vcc
	v_lshl_add_u64 v[60:61], s[8:9], 1, v[4:5]
	v_and_b32_e32 v16, 3, v53
	v_lshlrev_b32_e32 v16, 4, v16
	v_mov_b32_e32 v17, 0
	v_lshl_add_u64 v[60:61], v[60:61], 0, v[16:17]
	v_readlane_b32 s11, v254, 0
	s_lshl_b32 s10, s1, 1
	v_add_co_u32_e32 v62, vcc, s67, v20
	v_lshl_add_u64 v[16:17], v[60:61], 0, s[10:11]
	s_nop 0
	v_addc_co_u32_e32 v63, vcc, 0, v21, vcc
	s_movk_i32 s10, 0x5000
	v_lshl_add_u64 v[8:9], v[16:17], 0, s[98:99]
	v_lshl_add_u64 v[12:13], v[8:9], 0, s[98:99]
	v_lshl_add_u64 v[4:5], v[12:13], 0, s[98:99]
	global_load_dwordx4 v[4:7], v[4:5], off
	global_load_dwordx4 v[12:15], v[12:13], off
	global_load_dwordx4 v[8:11], v[8:9], off
	s_nop 0
	global_load_dwordx4 v[16:19], v[16:17], off
	s_nop 0
	global_load_dwordx2 v[64:65], v[30:31], off
	global_load_dword v196, v[32:33], off
	global_load_dword v189, v[34:35], off
	global_load_dwordx2 v[66:67], v[62:63], off
	v_add_co_u32_e32 v30, vcc, s10, v24
	s_mov_b32 s9, 0xa000
	s_nop 0
	v_addc_co_u32_e32 v31, vcc, 0, v25, vcc
	v_add_co_u32_e32 v32, vcc, s10, v22
	s_mov_b32 s1, 0x8000
	s_nop 0
	v_addc_co_u32_e32 v33, vcc, 0, v23, vcc
	v_add_co_u32_e32 v34, vcc, s9, v20
	s_movk_i32 s12, 0x3000
	s_nop 0
	v_addc_co_u32_e32 v35, vcc, 0, v21, vcc
	v_add_co_u32_e32 v68, vcc, s66, v24
	s_movk_i32 s13, 0x1000
	s_nop 0
	v_addc_co_u32_e32 v69, vcc, 0, v25, vcc
	v_add_co_u32_e32 v70, vcc, s66, v22
	v_ashrrev_i32_e32 v57, 31, v56
	s_nop 0
	v_addc_co_u32_e32 v71, vcc, 0, v23, vcc
	global_load_dword v198, v[30:31], off
	global_load_dword v192, v[32:33], off
	global_load_dwordx2 v[62:63], v[34:35], off
	global_load_dword v197, v[68:69], off
	global_load_dword v190, v[70:71], off
	v_add_co_u32_e32 v30, vcc, s1, v20
	v_lshlrev_b64 v[78:79], 11, v[56:57]
	s_nop 0
	v_addc_co_u32_e32 v31, vcc, 0, v21, vcc
	v_add_co_u32_e32 v32, vcc, s12, v24
	v_lshl_add_u64 v[78:79], v[78:79], 0, v[58:59]
	s_nop 0
	v_addc_co_u32_e32 v33, vcc, 0, v25, vcc
	v_add_co_u32_e32 v34, vcc, s12, v22
	v_lshlrev_b64 v[80:81], 1, v[78:79]
	s_nop 0
	v_addc_co_u32_e32 v35, vcc, 0, v23, vcc
	v_add_co_u32_e32 v68, vcc, s63, v20
	v_lshl_add_u64 v[82:83], s[72:73], 0, v[80:81]
	s_nop 0
	v_addc_co_u32_e32 v69, vcc, 0, v21, vcc
	global_load_dwordx2 v[70:71], v[30:31], off
	global_load_dword v200, v[32:33], off
	global_load_dword v191, v[34:35], off
	global_load_dwordx2 v[72:73], v[68:69], off
	v_add_co_u32_e32 v30, vcc, s69, v24
	v_lshl_add_u64 v[80:81], s[64:65], 0, v[80:81]
	s_nop 0
	v_addc_co_u32_e32 v31, vcc, 0, v25, vcc
	v_add_co_u32_e32 v32, vcc, s69, v22
	v_lshl_add_u64 v[78:79], v[78:79], 2, s[74:75]
	s_nop 0
	v_addc_co_u32_e32 v33, vcc, 0, v23, vcc
	v_add_co_u32_e32 v34, vcc, s66, v20
	v_xor_b32_e32 v57, 1, v208
	s_nop 0
	v_addc_co_u32_e32 v35, vcc, 0, v21, vcc
	v_add_co_u32_e32 v68, vcc, s13, v24
	s_mov_b32 s28, 0xe000
	s_nop 0
	v_addc_co_u32_e32 v69, vcc, 0, v25, vcc
	v_add_co_u32_e32 v74, vcc, s13, v22
	s_mov_b32 s47, 0x8000
	s_nop 0
	v_addc_co_u32_e32 v75, vcc, 0, v23, vcc
	global_load_dword v202, v[30:31], off
	global_load_dword v195, v[32:33], off
	global_load_dwordx2 v[76:77], v[34:35], off
	global_load_dword v215, v[68:69], off
	global_load_dword v194, v[74:75], off
	v_add_co_u32_e32 v74, vcc, s69, v20
	s_mov_b32 s24, 0
	s_nop 0
	v_addc_co_u32_e32 v75, vcc, 0, v21, vcc
	v_add_co_u32_e32 v84, vcc, s33, v82
	global_load_dword v225, v[26:27], off
	global_load_dword v199, v[28:29], off
	global_load_dwordx2 v[68:69], v[20:21], off
	global_load_dword v193, v[22:23], off
	global_load_dword v201, v[24:25], off
	s_nop 0
	v_lshl_add_u64 v[24:25], v[60:61], 0, s[98:99]
	v_lshl_add_u64 v[28:29], v[24:25], 0, s[98:99]
	v_lshl_add_u64 v[20:21], v[28:29], 0, s[98:99]
	global_load_dwordx4 v[20:23], v[20:21], off
	global_load_dwordx4 v[28:31], v[28:29], off
	global_load_dwordx4 v[24:27], v[24:25], off
	global_load_dwordx4 v[32:35], v[60:61], off
	v_addc_co_u32_e32 v85, vcc, 0, v83, vcc
	v_add_co_u32_e32 v86, vcc, s33, v80
	v_add_u32_e32 v217, s8, v175
	s_nop 0
	v_addc_co_u32_e32 v87, vcc, 0, v81, vcc
	v_add_co_u32_e32 v88, vcc, s3, v78
	s_mov_b32 s3, 0xa000
	s_nop 0
	v_addc_co_u32_e32 v89, vcc, 0, v79, vcc
	v_add_co_u32_e32 v92, vcc, s63, v82
	s_add_i32 s21, s8, 32
	s_nop 0
	v_addc_co_u32_e32 v93, vcc, 0, v83, vcc
	v_add_co_u32_e32 v94, vcc, s63, v80
	s_sub_i32 s22, s17, 32
	s_nop 0
	v_addc_co_u32_e32 v95, vcc, 0, v81, vcc
	v_add_co_u32_e32 v90, vcc, s67, v78
	v_mov_b32_e32 v112, 0
	s_nop 0
	v_addc_co_u32_e32 v91, vcc, 0, v79, vcc
	v_add_co_u32_e32 v96, vcc, s10, v82
	v_mov_b32_e32 v113, 0
	s_nop 0
	v_addc_co_u32_e32 v97, vcc, 0, v83, vcc
	v_add_co_u32_e32 v98, vcc, s10, v80
	s_lshl_b32 s10, s0, 9
	s_nop 0
	v_addc_co_u32_e32 v99, vcc, 0, v81, vcc
	v_add_co_u32_e32 v100, vcc, s9, v78
	s_mov_b32 s9, 1
	s_nop 0
	v_addc_co_u32_e32 v101, vcc, 0, v79, vcc
	global_load_dwordx2 v[108:109], v[90:91], off
	global_load_dword v229, v[96:97], off
	global_load_dword v221, v[98:99], off
	s_nop 0
	global_load_dwordx2 v[90:91], v[100:101], off
	v_add_co_u32_e32 v96, vcc, s66, v82
	v_mov_b32_e32 v120, 0
	s_nop 0
	v_addc_co_u32_e32 v97, vcc, 0, v83, vcc
	v_add_co_u32_e32 v98, vcc, s66, v80
	v_mov_b32_e32 v121, 0
	s_nop 0
	v_addc_co_u32_e32 v99, vcc, 0, v81, vcc
	v_add_co_u32_e32 v100, vcc, s1, v78
	s_mov_b32 s1, s11
	s_nop 0
	v_addc_co_u32_e32 v101, vcc, 0, v79, vcc
	v_add_co_u32_e32 v102, vcc, s12, v82
	v_writelane_b32 v253, s0, 63
	s_nop 0
	v_addc_co_u32_e32 v103, vcc, 0, v83, vcc
	v_add_co_u32_e32 v104, vcc, s12, v80
	v_writelane_b32 v254, s1, 0
	s_nop 0
	v_addc_co_u32_e32 v105, vcc, 0, v81, vcc
	global_load_dword v231, v[96:97], off
	global_load_dword v223, v[98:99], off
	s_nop 0
	global_load_dwordx2 v[100:101], v[100:101], off
	s_nop 0
	global_load_dword v232, v[102:103], off
	global_load_dword v222, v[104:105], off
	v_add_co_u32_e32 v96, vcc, s63, v78
	v_mov_b32_e32 v124, 0
	s_nop 0
	v_addc_co_u32_e32 v97, vcc, 0, v79, vcc
	v_add_co_u32_e32 v98, vcc, s69, v82
	v_mov_b32_e32 v125, 0
	s_nop 0
	v_addc_co_u32_e32 v99, vcc, 0, v83, vcc
	v_add_co_u32_e32 v102, vcc, s69, v80
	v_mov_b32_e32 v110, 0
	s_nop 0
	v_addc_co_u32_e32 v103, vcc, 0, v81, vcc
	v_add_co_u32_e32 v104, vcc, s66, v78
	v_mov_b32_e32 v111, 0
	s_nop 0
	v_addc_co_u32_e32 v105, vcc, 0, v79, vcc
	global_load_dwordx2 v[114:115], v[96:97], off
	global_load_dword v234, v[98:99], off
	global_load_dword v226, v[102:103], off
	global_load_dwordx2 v[118:119], v[104:105], off
	v_add_co_u32_e32 v96, vcc, s13, v82
	v_mov_b32_e32 v116, 0
	s_nop 0
	v_addc_co_u32_e32 v97, vcc, 0, v83, vcc
	v_add_co_u32_e32 v98, vcc, s13, v80
	v_mov_b32_e32 v117, 0
	s_nop 0
	v_addc_co_u32_e32 v99, vcc, 0, v81, vcc
	v_add_co_u32_e32 v102, vcc, s69, v78
	v_mov_b32_e32 v122, 0
	s_nop 0
	v_addc_co_u32_e32 v103, vcc, 0, v79, vcc
	global_load_dword v235, v[96:97], off
	global_load_dword v227, v[98:99], off
	s_nop 0
	global_load_dwordx2 v[102:103], v[102:103], off
	s_nop 0
	global_load_dwordx2 v[104:105], v[74:75], off
	global_load_dword v237, v[84:85], off
	global_load_dword v230, v[86:87], off
	global_load_dword v224, v[80:81], off
	global_load_dword v233, v[82:83], off
	global_load_dwordx2 v[128:129], v[88:89], off
	global_load_dword v236, v[92:93], off
	global_load_dword v228, v[94:95], off
	global_load_dwordx2 v[106:107], v[78:79], off
	v_and_b32_e32 v80, 64, v208
	v_add_u32_e32 v74, 64, v80
	v_cmp_lt_i32_e32 vcc, v57, v74
	v_xor_b32_e32 v75, 2, v208
	v_add_u32_e32 v81, -16, v208
	v_cndmask_b32_e32 v57, v208, v57, vcc
	v_cmp_lt_i32_e32 vcc, v75, v74
	v_lshlrev_b32_e32 v57, 2, v57
	v_lshl_add_u64 v[78:79], v[38:39], 0, s[10:11]
	v_cndmask_b32_e32 v75, v208, v75, vcc
	v_lshlrev_b32_e32 v203, 2, v75
	v_xor_b32_e32 v75, 4, v208
	v_cmp_lt_i32_e32 vcc, v75, v74
	v_mov_b32_e32 v84, 0
	v_mov_b32_e32 v85, 0
	v_cndmask_b32_e32 v74, v208, v75, vcc
	v_cmp_lt_i32_e32 vcc, v81, v80
	v_lshlrev_b32_e32 v216, 2, v74
	v_lshl_add_u64 v[74:75], v[36:37], 0, s[10:11]
	v_cndmask_b32_e32 v81, v81, v208, vcc
	v_lshlrev_b32_e32 v218, 2, v81
	v_subrev_u32_e32 v81, 32, v208
	v_cmp_lt_i32_e32 vcc, v81, v80
	v_or_b32_e32 v80, v80, v0
	v_lshl_or_b32 v220, v80, 2, v209
	v_cndmask_b32_e32 v81, v81, v208, vcc
	v_lshlrev_b32_e32 v219, 2, v81
	v_mov_b32_e32 v80, 0
	v_mov_b32_e32 v81, 0
	v_mov_b32_e32 v88, 0
	v_mov_b32_e32 v89, 0
	v_mov_b32_e32 v94, 0
	v_mov_b32_e32 v95, 0
	v_mov_b32_e32 v98, 0
	v_mov_b32_e32 v99, 0
	v_mov_b32_e32 v82, 0
	v_mov_b32_e32 v83, 0
	v_mov_b32_e32 v86, 0
	v_mov_b32_e32 v87, 0
	v_mov_b32_e32 v92, 0
	v_mov_b32_e32 v93, 0
	v_mov_b32_e32 v96, 0
	v_mov_b32_e32 v97, 0
	v_mov_b32_e32 v123, 0
	v_mov_b32_e32 v126, 0
	v_mov_b32_e32 v127, 0
	s_mov_b32 s23, s17
	s_waitcnt vmcnt(0)
	s_branch .LBB0_291

.LBB0_295:
	ds_read_b128 v[130:133], v188
	ds_read_b128 v[134:137], v188 offset:128
	ds_read_b128 v[138:141], v188 offset:256
	ds_read_b128 v[142:145], v188 offset:384
	ds_read_b128 v[146:149], v188 offset:512
	ds_read_b128 v[150:153], v188 offset:640
	ds_read_b128 v[154:157], v188 offset:768
	ds_read_b128 v[166:169], v188 offset:896
	s_sub_i32 s0, s8, s25
	v_cmp_gt_i32_e32 vcc, s26, v175
	s_min_i32 s1, s24, s20
	s_lshl_b32 s1, s1, 5
	s_sub_i32 s25, s17, s1
	v_lshlrev_b32_e32 v172, 16, v126
	v_and_b32_e32 v173, 0xffff0000, v126
	s_cmp_gt_i32 s25, 31
	s_waitcnt lgkmcnt(6)
	v_mul_f32_e32 v238, v130, v130
	v_mul_f32_e32 v239, v131, v131
	v_mul_f32_e32 v240, v132, v132
	v_mul_f32_e32 v241, v133, v133
	v_fmac_f32_e32 v238, v134, v134
	v_fmac_f32_e32 v239, v135, v135
	v_fmac_f32_e32 v240, v136, v136
	v_fmac_f32_e32 v241, v137, v137
	s_waitcnt lgkmcnt(4)
	v_fmac_f32_e32 v238, v138, v138
	v_fmac_f32_e32 v239, v139, v139
	v_fmac_f32_e32 v240, v140, v140
	v_fmac_f32_e32 v241, v141, v141
	v_fmac_f32_e32 v238, v142, v142
	v_fmac_f32_e32 v239, v143, v143
	v_fmac_f32_e32 v240, v144, v144
	v_fmac_f32_e32 v241, v145, v145
	s_waitcnt lgkmcnt(2)
	v_fmac_f32_e32 v238, v146, v146
	v_fmac_f32_e32 v239, v147, v147
	v_fmac_f32_e32 v240, v148, v148
	v_fmac_f32_e32 v241, v149, v149
	v_fmac_f32_e32 v238, v150, v150
	v_fmac_f32_e32 v239, v151, v151
	v_fmac_f32_e32 v240, v152, v152
	v_fmac_f32_e32 v241, v153, v153
	s_waitcnt lgkmcnt(0)
	v_fmac_f32_e32 v238, v154, v154
	v_fmac_f32_e32 v239, v155, v155
	v_fmac_f32_e32 v240, v156, v156
	v_fmac_f32_e32 v241, v157, v157
	v_fmac_f32_e32 v238, v166, v166
	v_fmac_f32_e32 v239, v167, v167
	v_fmac_f32_e32 v240, v168, v168
	v_fmac_f32_e32 v241, v169, v169
	v_add_f32_e32 v238, v238, v239
	v_add_f32_e32 v240, v240, v241
	v_add_f32_e32 v158, v238, v240
	s_nop 1
	v_add_f32_dpp v158, v158, v158 quad_perm:[1,0,3,2] row_mask:0xf bank_mask:0xf
	s_nop 1
	v_add_f32_dpp v158, v158, v158 quad_perm:[2,3,0,1] row_mask:0xf bank_mask:0xf
	s_nop 1
	v_add_f32_dpp v158, v158, v158 row_half_mirror row_mask:0xf bank_mask:0xf
	v_fmamk_f32 v158, v158, 0x3b800000, v206
	v_rsq_f32_e32 v158, v158
	v_mov_b32_e32 v159, s0
	v_cndmask_b32_e32 v159, v210, v159, vcc
	v_add_u32_e32 v170, v159, v175
	v_pk_mul_f32 v[130:131], v[130:131], v[158:159] op_sel_hi:[1,0]
	v_ashrrev_i32_e32 v171, 31, v170
	v_pk_mul_f32 v[130:131], v[130:131], v[172:173]
	v_lshlrev_b64 v[170:171], 13, v[170:171]
	v_cvt_pk_bf16_f32 v126, v130, v131
	v_pk_mul_f32 v[130:131], v[132:133], v[158:159] op_sel_hi:[1,0]
	v_lshlrev_b32_e32 v132, 16, v127
	v_and_b32_e32 v133, 0xffff0000, v127
	v_pk_mul_f32 v[130:131], v[130:131], v[132:133]
	v_lshl_add_u64 v[170:171], v[74:75], 0, v[170:171]
	v_cvt_pk_bf16_f32 v127, v130, v131
	global_store_dwordx2 v[170:171], v[126:127], off
	v_pk_mul_f32 v[126:127], v[134:135], v[158:159] op_sel_hi:[1,0]
	v_lshlrev_b32_e32 v130, 16, v122
	v_and_b32_e32 v131, 0xffff0000, v122
	v_pk_mul_f32 v[126:127], v[126:127], v[130:131]
	v_lshlrev_b32_e32 v130, 16, v123
	v_cvt_pk_bf16_f32 v122, v126, v127
	v_pk_mul_f32 v[126:127], v[136:137], v[158:159] op_sel_hi:[1,0]
	v_and_b32_e32 v131, 0xffff0000, v123
	v_pk_mul_f32 v[126:127], v[126:127], v[130:131]
	s_nop 0
	v_cvt_pk_bf16_f32 v123, v126, v127
	global_store_dwordx2 v[170:171], v[122:123], off offset:64
	v_pk_mul_f32 v[122:123], v[138:139], v[158:159] op_sel_hi:[1,0]
	v_lshlrev_b32_e32 v126, 16, v116
	v_and_b32_e32 v127, 0xffff0000, v116
	v_pk_mul_f32 v[122:123], v[122:123], v[126:127]
	v_lshlrev_b32_e32 v126, 16, v117
	v_cvt_pk_bf16_f32 v116, v122, v123
	v_pk_mul_f32 v[122:123], v[140:141], v[158:159] op_sel_hi:[1,0]
	v_and_b32_e32 v127, 0xffff0000, v117
	v_pk_mul_f32 v[122:123], v[122:123], v[126:127]
	s_nop 0
	v_cvt_pk_bf16_f32 v117, v122, v123
	global_store_dwordx2 v[170:171], v[116:117], off offset:128
	v_pk_mul_f32 v[116:117], v[142:143], v[158:159] op_sel_hi:[1,0]
	v_lshlrev_b32_e32 v122, 16, v110
	v_and_b32_e32 v123, 0xffff0000, v110
	v_pk_mul_f32 v[116:117], v[116:117], v[122:123]
	v_lshlrev_b32_e32 v122, 16, v111
	v_cvt_pk_bf16_f32 v110, v116, v117
	v_pk_mul_f32 v[116:117], v[144:145], v[158:159] op_sel_hi:[1,0]
	v_and_b32_e32 v123, 0xffff0000, v111
	v_pk_mul_f32 v[116:117], v[116:117], v[122:123]
	s_nop 0
	v_cvt_pk_bf16_f32 v111, v116, v117
	global_store_dwordx2 v[170:171], v[110:111], off offset:192
	v_pk_mul_f32 v[110:111], v[146:147], v[158:159] op_sel_hi:[1,0]
	v_lshlrev_b32_e32 v116, 16, v96
	v_and_b32_e32 v117, 0xffff0000, v96
	v_pk_mul_f32 v[110:111], v[110:111], v[116:117]
	v_lshlrev_b32_e32 v116, 16, v97
	v_cvt_pk_bf16_f32 v96, v110, v111
	v_pk_mul_f32 v[110:111], v[148:149], v[158:159] op_sel_hi:[1,0]
	v_and_b32_e32 v117, 0xffff0000, v97
	v_pk_mul_f32 v[110:111], v[110:111], v[116:117]
	s_nop 0
	v_cvt_pk_bf16_f32 v97, v110, v111
	global_store_dwordx2 v[170:171], v[96:97], off offset:256
	v_pk_mul_f32 v[96:97], v[150:151], v[158:159] op_sel_hi:[1,0]
	v_lshlrev_b32_e32 v110, 16, v92
	v_and_b32_e32 v111, 0xffff0000, v92
	v_pk_mul_f32 v[96:97], v[96:97], v[110:111]
	v_lshlrev_b32_e32 v110, 16, v93
	v_cvt_pk_bf16_f32 v92, v96, v97
	v_pk_mul_f32 v[96:97], v[152:153], v[158:159] op_sel_hi:[1,0]
	v_and_b32_e32 v111, 0xffff0000, v93
	v_pk_mul_f32 v[96:97], v[96:97], v[110:111]
	s_nop 0
	v_cvt_pk_bf16_f32 v93, v96, v97
	global_store_dwordx2 v[170:171], v[92:93], off offset:320
	v_pk_mul_f32 v[92:93], v[154:155], v[158:159] op_sel_hi:[1,0]
	v_lshlrev_b32_e32 v96, 16, v86
	v_and_b32_e32 v97, 0xffff0000, v86
	v_pk_mul_f32 v[92:93], v[92:93], v[96:97]
	v_lshlrev_b32_e32 v96, 16, v87
	v_cvt_pk_bf16_f32 v86, v92, v93
	v_pk_mul_f32 v[92:93], v[156:157], v[158:159] op_sel_hi:[1,0]
	v_and_b32_e32 v97, 0xffff0000, v87
	v_pk_mul_f32 v[92:93], v[92:93], v[96:97]
	s_nop 0
	v_cvt_pk_bf16_f32 v87, v92, v93
	global_store_dwordx2 v[170:171], v[86:87], off offset:384
	v_pk_mul_f32 v[86:87], v[166:167], v[158:159] op_sel_hi:[1,0]
	v_lshlrev_b32_e32 v92, 16, v82
	v_and_b32_e32 v93, 0xffff0000, v82
	v_pk_mul_f32 v[86:87], v[86:87], v[92:93]
	v_lshlrev_b32_e32 v92, 16, v83
	v_cvt_pk_bf16_f32 v82, v86, v87
	v_pk_mul_f32 v[86:87], v[168:169], v[158:159] op_sel_hi:[1,0]
	v_and_b32_e32 v93, 0xffff0000, v83
	v_pk_mul_f32 v[86:87], v[86:87], v[92:93]
	s_waitcnt vmcnt(51)
	v_lshlrev_b32_e32 v168, 16, v232
	v_cvt_pk_bf16_f32 v83, v86, v87
	global_store_dwordx2 v[170:171], v[82:83], off offset:448
	v_add_u32_e32 v82, s1, v217
	v_ashrrev_i32_e32 v83, 31, v82
	v_lshlrev_b64 v[82:83], 13, v[82:83]
	v_lshl_add_u64 v[82:83], v[78:79], 0, v[82:83]
	global_load_dwordx2 v[126:127], v[82:83], off
	global_load_dwordx2 v[122:123], v[82:83], off offset:64
	global_load_dwordx2 v[116:117], v[82:83], off offset:128
	global_load_dwordx2 v[110:111], v[82:83], off offset:192
	global_load_dwordx2 v[96:97], v[82:83], off offset:256
	global_load_dwordx2 v[92:93], v[82:83], off offset:320
	global_load_dwordx2 v[86:87], v[82:83], off offset:384
	s_nop 0
	global_load_dwordx2 v[82:83], v[82:83], off offset:448
	s_mov_b64 s[0:1], -1
	v_lshlrev_b32_e32 v170, 16, v234
	v_lshlrev_b32_e32 v166, 16, v231
	v_lshlrev_b32_e32 v158, 16, v229
	s_cbranch_scc1 .LBB0_297
	s_min_i32 s0, s25, 32
	v_add_f32_e32 v130, 0, v106
	v_cmp_gt_i32_e32 vcc, s0, v176
	v_and_b32_e32 v132, 0xffff0000, v235
	v_and_b32_e32 v134, 0xffff0000, v234
	v_cndmask_b32_e32 v136, 0, v130, vcc
	v_add_f32_e32 v130, 0, v107
	v_cndmask_b32_e32 v139, 0, v130, vcc
	v_lshlrev_b32_e32 v130, 16, v233
	v_cndmask_b32_e32 v131, 0, v130, vcc
	v_and_b32_e32 v130, 0xffff0000, v233
	v_cndmask_b32_e32 v241, 0, v130, vcc
	v_cmp_gt_i32_e32 vcc, s0, v1
	v_lshlrev_b32_e32 v130, 16, v235
	v_and_b32_e32 v135, 0xffff0000, v232
	v_cndmask_b32_e32 v133, 0, v102, vcc
	v_add_f32_e32 v138, v136, v133
	v_cndmask_b32_e32 v239, 0, v130, vcc
	v_cndmask_b32_e32 v240, 0, v132, vcc
	v_cndmask_b32_e32 v133, 0, v103, vcc
	v_cmp_gt_i32_e32 vcc, s0, v40
	v_and_b32_e32 v137, 0xffff0000, v231
	v_and_b32_e32 v140, 0xffff0000, v229
	v_cndmask_b32_e32 v132, 0, v118, vcc
	v_cmp_gt_i32_e32 vcc, s0, v41
	v_pk_add_f32 v[146:147], v[132:133], v[138:139]
	v_lshlrev_b32_e32 v159, 16, v236
	v_cndmask_b32_e32 v157, 0, v134, vcc
	v_cndmask_b32_e32 v156, 0, v170, vcc
	v_cndmask_b32_e32 v133, 0, v119, vcc
	v_cmp_gt_i32_e32 vcc, s0, v54
	v_lshlrev_b32_e32 v162, 16, v237
	v_and_b32_e32 v163, 0xffff0000, v236
	v_cndmask_b32_e32 v132, 0, v114, vcc
	v_cmp_gt_i32_e32 vcc, s0, v3
	v_pk_add_f32 v[148:149], v[132:133], v[146:147]
	s_nop 0
	v_cndmask_b32_e32 v155, 0, v135, vcc
	v_cndmask_b32_e32 v154, 0, v168, vcc
	v_cndmask_b32_e32 v133, 0, v115, vcc
	v_cmp_gt_i32_e32 vcc, s0, v52
	s_nop 1
	v_cndmask_b32_e32 v132, 0, v100, vcc
	v_cmp_gt_i32_e32 vcc, s0, v43
	v_pk_add_f32 v[142:143], v[132:133], v[148:149]
	s_nop 0
	v_cndmask_b32_e32 v153, 0, v137, vcc
	v_cndmask_b32_e32 v152, 0, v166, vcc
	v_cndmask_b32_e32 v133, 0, v101, vcc
	v_cmp_gt_i32_e32 vcc, s0, v42
	s_nop 1
	v_cndmask_b32_e32 v132, 0, v90, vcc
	v_cmp_gt_i32_e32 vcc, s0, v51
	v_pk_add_f32 v[144:145], v[132:133], v[142:143]
	s_nop 0
	v_cndmask_b32_e32 v151, 0, v140, vcc
	v_cndmask_b32_e32 v150, 0, v158, vcc
	v_cndmask_b32_e32 v133, 0, v91, vcc
	v_cmp_gt_i32_e32 vcc, s0, v50
	s_nop 1
	v_cndmask_b32_e32 v132, 0, v108, vcc
	v_cmp_gt_i32_e32 vcc, s0, v45
	v_cmp_gt_i32_e64 s[0:1], s0, v44
	v_pk_add_f32 v[140:141], v[132:133], v[144:145]
	v_cndmask_b32_e32 v133, 0, v109, vcc
	v_cndmask_b32_e64 v132, 0, v128, s[0:1]
	v_cndmask_b32_e32 v130, 0, v159, vcc
	v_pk_add_f32 v[134:135], v[132:133], v[140:141]
	v_cndmask_b32_e64 v132, 0, v129, s[0:1]
	v_and_b32_e32 v159, 0xffff0000, v237
	v_add_f32_e32 v137, v132, v135
	v_cndmask_b32_e32 v133, 0, v163, vcc
	v_cndmask_b32_e64 v132, 0, v162, s[0:1]
	v_cndmask_b32_e64 v238, 0, v159, s[0:1]
	s_mov_b64 s[0:1], 0

.LBB0_305:
	ds_read_b128 v[130:133], v188 offset:33280
	ds_read_b128 v[134:137], v188 offset:33408
	ds_read_b128 v[138:141], v188 offset:33536
	ds_read_b128 v[142:145], v188 offset:33664
	ds_read_b128 v[146:149], v188 offset:33792
	ds_read_b128 v[150:153], v188 offset:33920
	ds_read_b128 v[154:157], v188 offset:34048
	ds_read_b128 v[166:169], v188 offset:34176
	s_sub_i32 s0, s21, s0
	v_cmp_gt_i32_e32 vcc, s1, v175
	s_add_i32 s10, s24, 1
	s_min_i32 s10, s10, s20
	v_lshlrev_b32_e32 v170, 16, v124
	v_and_b32_e32 v171, 0xffff0000, v124
	s_lshl_b32 s10, s10, 5
	s_waitcnt lgkmcnt(6)
	v_mul_f32_e32 v238, v130, v130
	v_mul_f32_e32 v239, v131, v131
	v_mul_f32_e32 v240, v132, v132
	v_mul_f32_e32 v241, v133, v133
	v_fmac_f32_e32 v238, v134, v134
	v_fmac_f32_e32 v239, v135, v135
	v_fmac_f32_e32 v240, v136, v136
	v_fmac_f32_e32 v241, v137, v137
	s_waitcnt lgkmcnt(4)
	v_fmac_f32_e32 v238, v138, v138
	v_fmac_f32_e32 v239, v139, v139
	v_fmac_f32_e32 v240, v140, v140
	v_fmac_f32_e32 v241, v141, v141
	v_fmac_f32_e32 v238, v142, v142
	v_fmac_f32_e32 v239, v143, v143
	v_fmac_f32_e32 v240, v144, v144
	v_fmac_f32_e32 v241, v145, v145
	s_waitcnt lgkmcnt(2)
	v_fmac_f32_e32 v238, v146, v146
	v_fmac_f32_e32 v239, v147, v147
	v_fmac_f32_e32 v240, v148, v148
	v_fmac_f32_e32 v241, v149, v149
	v_fmac_f32_e32 v238, v150, v150
	v_fmac_f32_e32 v239, v151, v151
	v_fmac_f32_e32 v240, v152, v152
	v_fmac_f32_e32 v241, v153, v153
	s_waitcnt lgkmcnt(0)
	v_fmac_f32_e32 v238, v154, v154
	v_fmac_f32_e32 v239, v155, v155
	v_fmac_f32_e32 v240, v156, v156
	v_fmac_f32_e32 v241, v157, v157
	v_fmac_f32_e32 v238, v166, v166
	v_fmac_f32_e32 v239, v167, v167
	v_fmac_f32_e32 v240, v168, v168
	v_fmac_f32_e32 v241, v169, v169
	v_add_f32_e32 v238, v238, v239
	v_add_f32_e32 v240, v240, v241
	v_add_f32_e32 v158, v238, v240
	s_nop 1
	v_add_f32_dpp v158, v158, v158 quad_perm:[1,0,3,2] row_mask:0xf bank_mask:0xf
	s_nop 1
	v_add_f32_dpp v158, v158, v158 quad_perm:[2,3,0,1] row_mask:0xf bank_mask:0xf
	s_nop 1
	v_add_f32_dpp v158, v158, v158 row_half_mirror row_mask:0xf bank_mask:0xf
	v_fmamk_f32 v158, v158, 0x3b800000, v206
	v_rsq_f32_e32 v158, v158
	v_mov_b32_e32 v159, s0
	v_cndmask_b32_e32 v159, v210, v159, vcc
	v_add_u32_e32 v162, v159, v175
	v_pk_mul_f32 v[130:131], v[130:131], v[158:159] op_sel_hi:[1,0]
	v_ashrrev_i32_e32 v163, 31, v162
	v_pk_mul_f32 v[130:131], v[130:131], v[170:171]
	v_lshlrev_b64 v[162:163], 13, v[162:163]
	v_cvt_pk_bf16_f32 v124, v130, v131
	v_pk_mul_f32 v[130:131], v[132:133], v[158:159] op_sel_hi:[1,0]
	v_lshlrev_b32_e32 v132, 16, v125
	v_and_b32_e32 v133, 0xffff0000, v125
	v_pk_mul_f32 v[130:131], v[130:131], v[132:133]
	v_lshl_add_u64 v[162:163], v[74:75], 0, v[162:163]
	v_cvt_pk_bf16_f32 v125, v130, v131
	global_store_dwordx2 v[162:163], v[124:125], off
	v_pk_mul_f32 v[124:125], v[134:135], v[158:159] op_sel_hi:[1,0]
	v_lshlrev_b32_e32 v130, 16, v120
	v_and_b32_e32 v131, 0xffff0000, v120
	v_pk_mul_f32 v[124:125], v[124:125], v[130:131]
	v_lshlrev_b32_e32 v130, 16, v121
	v_cvt_pk_bf16_f32 v120, v124, v125
	v_pk_mul_f32 v[124:125], v[136:137], v[158:159] op_sel_hi:[1,0]
	v_and_b32_e32 v131, 0xffff0000, v121
	v_pk_mul_f32 v[124:125], v[124:125], v[130:131]
	s_mov_b64 s[0:1], -1
	v_cvt_pk_bf16_f32 v121, v124, v125
	global_store_dwordx2 v[162:163], v[120:121], off offset:64
	v_pk_mul_f32 v[120:121], v[138:139], v[158:159] op_sel_hi:[1,0]
	v_lshlrev_b32_e32 v124, 16, v112
	v_and_b32_e32 v125, 0xffff0000, v112
	v_pk_mul_f32 v[120:121], v[120:121], v[124:125]
	v_lshlrev_b32_e32 v124, 16, v113
	v_cvt_pk_bf16_f32 v112, v120, v121
	v_pk_mul_f32 v[120:121], v[140:141], v[158:159] op_sel_hi:[1,0]
	v_and_b32_e32 v125, 0xffff0000, v113
	v_pk_mul_f32 v[120:121], v[120:121], v[124:125]
	s_nop 0
	v_cvt_pk_bf16_f32 v113, v120, v121
	global_store_dwordx2 v[162:163], v[112:113], off offset:128
	v_pk_mul_f32 v[112:113], v[142:143], v[158:159] op_sel_hi:[1,0]
	v_lshlrev_b32_e32 v120, 16, v98
	v_and_b32_e32 v121, 0xffff0000, v98
	v_pk_mul_f32 v[112:113], v[112:113], v[120:121]
	v_lshlrev_b32_e32 v120, 16, v99
	v_cvt_pk_bf16_f32 v98, v112, v113
	v_pk_mul_f32 v[112:113], v[144:145], v[158:159] op_sel_hi:[1,0]
	v_and_b32_e32 v121, 0xffff0000, v99
	v_pk_mul_f32 v[112:113], v[112:113], v[120:121]
	s_nop 0
	v_cvt_pk_bf16_f32 v99, v112, v113
	global_store_dwordx2 v[162:163], v[98:99], off offset:192
	v_pk_mul_f32 v[98:99], v[146:147], v[158:159] op_sel_hi:[1,0]
	v_lshlrev_b32_e32 v112, 16, v94
	v_and_b32_e32 v113, 0xffff0000, v94
	v_pk_mul_f32 v[98:99], v[98:99], v[112:113]
	v_lshlrev_b32_e32 v112, 16, v95
	v_cvt_pk_bf16_f32 v94, v98, v99
	v_pk_mul_f32 v[98:99], v[148:149], v[158:159] op_sel_hi:[1,0]
	v_and_b32_e32 v113, 0xffff0000, v95
	v_pk_mul_f32 v[98:99], v[98:99], v[112:113]
	s_nop 0
	v_cvt_pk_bf16_f32 v95, v98, v99
	global_store_dwordx2 v[162:163], v[94:95], off offset:256
	v_pk_mul_f32 v[94:95], v[150:151], v[158:159] op_sel_hi:[1,0]
	v_lshlrev_b32_e32 v98, 16, v88
	v_and_b32_e32 v99, 0xffff0000, v88
	v_pk_mul_f32 v[94:95], v[94:95], v[98:99]
	v_lshlrev_b32_e32 v98, 16, v89
	v_cvt_pk_bf16_f32 v88, v94, v95
	v_pk_mul_f32 v[94:95], v[152:153], v[158:159] op_sel_hi:[1,0]
	v_and_b32_e32 v99, 0xffff0000, v89
	v_pk_mul_f32 v[94:95], v[94:95], v[98:99]
	s_nop 0
	v_cvt_pk_bf16_f32 v89, v94, v95
	global_store_dwordx2 v[162:163], v[88:89], off offset:320
	v_pk_mul_f32 v[88:89], v[154:155], v[158:159] op_sel_hi:[1,0]
	v_lshlrev_b32_e32 v94, 16, v84
	v_and_b32_e32 v95, 0xffff0000, v84
	v_pk_mul_f32 v[88:89], v[88:89], v[94:95]
	v_lshlrev_b32_e32 v94, 16, v85
	v_cvt_pk_bf16_f32 v84, v88, v89
	v_pk_mul_f32 v[88:89], v[156:157], v[158:159] op_sel_hi:[1,0]
	v_and_b32_e32 v95, 0xffff0000, v85
	v_pk_mul_f32 v[88:89], v[88:89], v[94:95]
	s_nop 0
	v_cvt_pk_bf16_f32 v85, v88, v89
	global_store_dwordx2 v[162:163], v[84:85], off offset:384
	v_pk_mul_f32 v[84:85], v[166:167], v[158:159] op_sel_hi:[1,0]
	v_lshlrev_b32_e32 v88, 16, v80
	v_and_b32_e32 v89, 0xffff0000, v80
	v_pk_mul_f32 v[84:85], v[84:85], v[88:89]
	v_lshlrev_b32_e32 v88, 16, v81
	v_cvt_pk_bf16_f32 v80, v84, v85
	v_pk_mul_f32 v[84:85], v[168:169], v[158:159] op_sel_hi:[1,0]
	v_and_b32_e32 v89, 0xffff0000, v81
	v_pk_mul_f32 v[84:85], v[84:85], v[88:89]
	s_nop 0
	v_cvt_pk_bf16_f32 v81, v84, v85
	global_store_dwordx2 v[162:163], v[80:81], off offset:448
	s_waitcnt vmcnt(51)
	v_add_u32_e32 v80, s10, v217
	v_ashrrev_i32_e32 v81, 31, v80
	v_lshlrev_b64 v[80:81], 13, v[80:81]
	v_lshl_add_u64 v[80:81], v[78:79], 0, v[80:81]
	global_load_dwordx2 v[124:125], v[80:81], off
	global_load_dwordx2 v[120:121], v[80:81], off offset:64
	global_load_dwordx2 v[112:113], v[80:81], off offset:128
	global_load_dwordx2 v[98:99], v[80:81], off offset:192
	global_load_dwordx2 v[94:95], v[80:81], off offset:256
	global_load_dwordx2 v[88:89], v[80:81], off offset:320
	global_load_dwordx2 v[84:85], v[80:81], off offset:384
	s_nop 0
	global_load_dwordx2 v[80:81], v[80:81], off offset:448
	s_sub_i32 s10, s17, s10
	s_cmp_gt_i32 s10, 31
	s_cbranch_scc1 .LBB0_307
	s_min_i32 s10, s10, 32
	v_add_f32_e32 v130, 0, v68
	v_cmp_gt_i32_e32 vcc, s10, v176
	v_cmp_gt_i32_e64 s[0:1], s10, v40
	v_and_b32_e32 v133, 0xffff0000, v215
	v_cndmask_b32_e32 v144, 0, v130, vcc
	v_add_f32_e32 v130, 0, v69
	v_cndmask_b32_e32 v143, 0, v130, vcc
	v_lshlrev_b32_e32 v130, 16, v201
	v_cndmask_b32_e32 v141, 0, v130, vcc
	v_and_b32_e32 v130, 0xffff0000, v201
	v_cndmask_b32_e32 v169, 0, v130, vcc
	v_cmp_gt_i32_e32 vcc, s10, v1
	v_lshlrev_b32_e32 v132, 16, v202
	v_cndmask_b32_e64 v138, 0, v132, s[0:1]
	v_cndmask_b32_e32 v130, 0, v104, vcc
	v_add_f32_e32 v142, v144, v130
	v_lshlrev_b32_e32 v130, 16, v215
	v_cndmask_b32_e32 v140, 0, v130, vcc
	v_cndmask_b32_e32 v131, 0, v105, vcc
	v_cndmask_b32_e64 v130, 0, v76, s[0:1]
	v_pk_add_f32 v[146:147], v[130:131], v[142:143]
	v_cndmask_b32_e64 v130, 0, v77, s[0:1]
	v_add_f32_e32 v241, v130, v147
	v_cndmask_b32_e32 v139, 0, v133, vcc
	v_and_b32_e32 v130, 0xffff0000, v202
	v_cmp_gt_i32_e32 vcc, s10, v3
	v_cndmask_b32_e64 v166, 0, v130, s[0:1]
	v_and_b32_e32 v131, 0xffff0000, v197
	v_cndmask_b32_e32 v130, 0, v72, vcc
	v_add_f32_e32 v239, v130, v146
	v_cndmask_b32_e32 v130, 0, v73, vcc
	v_add_f32_e32 v240, v130, v241
	v_lshlrev_b32_e32 v130, 16, v200
	v_cndmask_b32_e32 v135, 0, v130, vcc
	v_and_b32_e32 v130, 0xffff0000, v200
	v_cndmask_b32_e32 v159, 0, v130, vcc
	v_cmp_gt_i32_e32 vcc, s10, v43
	v_cmp_gt_i32_e64 s[0:1], s10, v42
	v_and_b32_e32 v133, 0xffff0000, v196
	v_cndmask_b32_e32 v130, 0, v70, vcc
	v_add_f32_e32 v173, v130, v239
	v_cndmask_b32_e32 v130, 0, v71, vcc
	v_add_f32_e32 v238, v130, v240
	v_lshlrev_b32_e32 v130, 16, v197
	v_cndmask_b32_e32 v134, 0, v130, vcc
	v_lshlrev_b32_e32 v130, 16, v198
	v_cndmask_b32_e64 v132, 0, v62, s[0:1]
	v_cndmask_b32_e32 v137, 0, v131, vcc
	v_cndmask_b32_e64 v136, 0, v130, s[0:1]
	v_and_b32_e32 v130, 0xffff0000, v198
	v_cmp_gt_i32_e32 vcc, s10, v45
	v_add_f32_e32 v171, v132, v173
	v_cndmask_b32_e64 v132, 0, v63, s[0:1]
	v_cndmask_b32_e64 v131, 0, v130, s[0:1]
	v_cndmask_b32_e32 v130, 0, v66, vcc
	v_add_f32_e32 v172, v132, v238
	v_add_f32_e32 v168, v130, v171
	v_cndmask_b32_e32 v130, 0, v67, vcc
	v_cmp_gt_i32_e64 s[0:1], s10, v44
	v_add_f32_e32 v170, v130, v172
	v_lshlrev_b32_e32 v130, 16, v196
	v_cndmask_b32_e64 v148, 0, v65, s[0:1]
	v_lshlrev_b32_e32 v132, 16, v225
	v_cndmask_b32_e64 v145, 0, v64, s[0:1]
	v_add_f32_e32 v167, v148, v170
	v_and_b32_e32 v148, 0xffff0000, v225
	v_cndmask_b32_e32 v130, 0, v130, vcc
	v_add_f32_e32 v145, v145, v168
	v_cndmask_b32_e32 v133, 0, v133, vcc
	v_cndmask_b32_e64 v132, 0, v132, s[0:1]
	v_cndmask_b32_e64 v158, 0, v148, s[0:1]
	s_mov_b64 s[0:1], 0

.LBB0_543:
	s_andn2_b64 vcc, exec, s[0:1]
	s_cbranch_vccnz .LBB0_589
	s_cmp_eq_u32 s50, 6
	s_cbranch_scc0 .LBB0_589
	s_waitcnt vmcnt(0)
	v_mov_b32_e32 v76, v204
	s_mov_b32 s51, s2
	v_readfirstlane_b32 s0, v76
	s_ashr_i32 s68, s0, 6
	v_readlane_b32 s0, v252, 20
	v_readlane_b32 s1, v252, 21
	s_andn2_b64 vcc, exec, s[0:1]
	s_movk_i32 s0, 0x500
	v_cmp_gt_i32_e64 s[0:1], s0, v76
	v_and_b32_e32 v103, 15, v76
	v_bfe_u32 v136, v76, 4, 2
	v_writelane_b32 v255, s0, 3
	v_lshlrev_b32_e32 v78, 2, v136
	v_or_b32_e32 v0, 0x80, v103
	v_writelane_b32 v255, s1, 4
	s_movk_i32 s0, 0x90
	v_lshlrev_b32_e32 v80, 4, v136
	v_mul_u32_u24_e32 v77, 0x150, v103
	v_mad_u32_u24 v79, v103, s0, 0
	v_sub_u32_e32 v137, v0, v78
	s_cbranch_vccnz .LBB0_566
	s_waitcnt lgkmcnt(0)
	v_min_i32_e32 v3, 0x4ff, v76
	v_ashrrev_i32_e32 v138, 3, v3
	v_readlane_b32 s2, v252, 22
	v_readlane_b32 s0, v252, 29
	s_mov_b32 s8, s0
	v_add_u32_e32 v0, s2, v138
	v_max_i32_e32 v0, 0, v0
	v_add_u32_e32 v0, s8, v0
	v_ashrrev_i32_e32 v1, 31, v0
	v_readlane_b32 s6, v252, 27
	v_lshlrev_b64 v[0:1], 10, v[0:1]
	v_readlane_b32 s7, v252, 28
	s_mov_b32 s3, 0x66666667
	v_mov_b32_e32 v7, v2
	v_lshl_add_u64 v[4:5], s[6:7], 0, v[0:1]
	v_lshlrev_b32_e32 v0, 3, v3
	v_and_b32_e32 v0, 56, v0
	v_lshlrev_b32_e32 v6, 1, v0
	v_mul_hi_i32 v1, v3, s3
	v_lshl_add_u64 v[4:5], v[4:5], 0, v[6:7]
	v_lshrrev_b32_e32 v6, 31, v1
	v_ashrrev_i32_e32 v1, 3, v1
	v_readlane_b32 s1, v252, 30
	v_add_u32_e32 v139, v1, v6
	s_movk_i32 s5, 0xffec
	v_mul_lo_u32 v1, v139, s5
	v_readlane_b32 s0, v252, 23
	v_add_lshl_u32 v140, v1, v3, 3
	v_readlane_b32 s1, v252, 24
	v_add_u32_e32 v1, s2, v140
	s_mov_b32 s4, s0
	v_readlane_b32 s0, v252, 33
	v_max_i32_e32 v1, 0, v1
	v_readlane_b32 s1, v252, 34
	v_add_u32_e32 v3, s4, v139
	v_lshlrev_b32_e32 v8, 1, v1
	v_mov_b64_e32 v[20:21], s[0:1]
	v_min_i32_e32 v1, 0x2ff, v76
	v_mad_i64_i32 v[6:7], s[0:1], v3, s93, v[20:21]
	v_add_u32_e32 v3, 0x200, v1
	v_ashrrev_i32_e32 v141, 3, v3
	v_add_u32_e32 v12, s2, v141
	v_max_i32_e32 v12, 0, v12
	v_add_u32_e32 v12, s8, v12
	v_ashrrev_i32_e32 v13, 31, v12
	v_lshlrev_b32_e32 v1, 3, v1
	v_lshlrev_b64 v[12:13], 10, v[12:13]
	v_and_b32_e32 v28, 56, v1
	v_lshl_add_u64 v[12:13], s[6:7], 0, v[12:13]
	v_lshlrev_b32_e32 v14, 1, v28
	v_mov_b32_e32 v15, v2
	v_mul_hi_i32 v1, v3, s3
	v_lshl_add_u64 v[12:13], v[12:13], 0, v[14:15]
	v_lshrrev_b32_e32 v14, 31, v1
	v_ashrrev_i32_e32 v1, 3, v1
	v_add_u32_e32 v142, v1, v14
	v_mul_lo_u32 v1, v142, s5
	v_add_lshl_u32 v143, v1, v3, 3
	v_add_u32_e32 v1, s2, v143
	v_max_i32_e32 v1, 0, v1
	v_add_u32_e32 v3, s4, v142
	v_lshlrev_b32_e32 v16, 1, v1
	v_min_i32_e32 v1, 0xff, v76
	v_mad_i64_i32 v[14:15], s[0:1], v3, s93, v[20:21]
	v_add_u32_e32 v3, 0x400, v1
	v_ashrrev_i32_e32 v144, 3, v3
	v_add_u32_e32 v22, s2, v144
	v_max_i32_e32 v22, 0, v22
	v_add_u32_e32 v22, s8, v22
	v_ashrrev_i32_e32 v23, 31, v22
	v_lshlrev_b32_e32 v1, 3, v1
	v_lshlrev_b64 v[22:23], 10, v[22:23]
	v_and_b32_e32 v30, 56, v1
	v_lshl_add_u64 v[22:23], s[6:7], 0, v[22:23]
	v_lshlrev_b32_e32 v24, 1, v30
	v_mov_b32_e32 v25, v2
	v_mul_hi_i32 v1, v3, s3
	v_lshl_add_u64 v[22:23], v[22:23], 0, v[24:25]
	v_lshrrev_b32_e32 v24, 31, v1
	v_ashrrev_i32_e32 v1, 3, v1
	v_add_u32_e32 v145, v1, v24
	v_mul_lo_u32 v1, v145, s5
	v_add_lshl_u32 v146, v1, v3, 3
	v_add_u32_e32 v1, s2, v146
	v_max_i32_e32 v1, 0, v1
	v_add_u32_e32 v3, s4, v145
	v_mov_b32_e32 v9, v2
	v_mov_b32_e32 v17, v2
	v_mad_i64_i32 v[20:21], s[0:1], v3, s93, v[20:21]
	v_lshlrev_b32_e32 v24, 1, v1
	v_lshl_add_u64 v[8:9], v[6:7], 0, v[8:9]
	v_lshl_add_u64 v[16:17], v[14:15], 0, v[16:17]
	v_lshl_add_u64 v[24:25], v[20:21], 0, v[24:25]
	global_load_dwordx4 v[4:7], v[4:5], off
	s_nop 0
	global_load_dwordx4 v[8:11], v[8:9], off
	s_nop 0
	global_load_dwordx4 v[12:15], v[12:13], off
	s_nop 0
	global_load_dwordx4 v[16:19], v[16:17], off
	s_nop 0
	global_load_dwordx4 v[20:23], v[22:23], off
	s_nop 0
	global_load_dwordx4 v[24:27], v[24:25], off
	v_mul_hi_i32 v29, v76, s3
	v_readlane_b32 s0, v251, 22
	v_lshrrev_b32_e32 v31, 31, v29
	v_ashrrev_i32_e32 v29, 3, v29
	v_lshlrev_b32_e32 v32, 3, v136
	v_mov_b32_e32 v33, v2
	v_readlane_b32 s1, v251, 23
	v_add_u32_e32 v29, v29, v31
	s_movk_i32 s4, 0x150
	v_lshl_add_u64 v[84:85], s[0:1], 0, v[32:33]
	v_mad_u64_u32 v[34:35], s[0:1], v29, s5, v[76:77]
	v_lshlrev_b32_e32 v147, 3, v34
	v_lshlrev_b32_e32 v31, 4, v34
	v_add_u32_e32 v34, 0x200, v76
	s_movk_i32 s0, 0x300
	v_mul_hi_i32 v35, v34, s3
	v_cmp_gt_i32_e64 s[0:1], s0, v76
	v_lshrrev_b32_e32 v37, 31, v35
	v_ashrrev_i32_e32 v35, 3, v35
	v_writelane_b32 v255, s0, 5
	v_add_u32_e32 v37, v35, v37
	v_ashrrev_i32_e32 v148, 3, v34
	v_writelane_b32 v255, s1, 6
	v_mad_u64_u32 v[34:35], s[0:1], v37, s5, v[34:35]
	v_lshlrev_b32_e32 v149, 3, v34
	v_mul_lo_u32 v35, v37, s4
	v_lshlrev_b32_e32 v38, 4, v34
	v_add_u32_e32 v34, 0x400, v76
	v_add_u32_e32 v37, 0, v35
	s_movk_i32 s0, 0x100
	v_mul_hi_i32 v35, v34, s3
	v_cmp_gt_i32_e64 s[0:1], s0, v76
	v_lshrrev_b32_e32 v40, 31, v35
	v_ashrrev_i32_e32 v35, 3, v35
	v_writelane_b32 v255, s0, 7
	v_add_u32_e32 v40, v35, v40
	v_ashrrev_i32_e32 v150, 3, v34
	v_writelane_b32 v255, s1, 8
	v_mad_u64_u32 v[34:35], s[0:1], v40, s5, v[34:35]
	v_readlane_b32 s0, v255, 1
	v_readlane_b32 s1, v255, 2
	s_lshl_b32 s0, s0, 6
	v_writelane_b32 v255, s0, 9
	v_readlane_b32 s0, v253, 53
	v_readlane_b32 s1, v253, 54
	v_mul_lo_u32 v29, v29, s4
	v_mul_lo_u32 v35, v40, s4
	v_lshl_add_u64 v[86:87], s[0:1], 0, v[32:33]
	s_movk_i32 s1, 0x80
	v_cmp_gt_u32_e64 s[4:5], s1, v137
	s_movk_i32 s0, 0x81
	v_add_u32_e32 v33, -3, v137
	v_writelane_b32 v255, s4, 10
	v_add_u32_e32 v40, 0, v32
	v_add_u32_e32 v32, -2, v137
	v_writelane_b32 v255, s5, 11
	v_cmp_gt_u32_e64 s[4:5], s0, v137
	s_movk_i32 s0, 0x7f
	v_or_b32_e32 v42, 0x90, v103
	v_writelane_b32 v255, s4, 12
	v_mov_b32_e32 v81, v2
	v_sub_u32_e32 v42, v42, v78
	v_writelane_b32 v255, s5, 13
	v_cmp_gt_u32_e64 s[4:5], s1, v33
	v_add_u32_e32 v33, 0xffffff7e, v137
	v_lshl_add_u64 v[82:83], s[64:65], 0, v[80:81]
	v_writelane_b32 v255, s4, 14
	v_ashrrev_i32_e32 v81, 3, v76
	s_movk_i32 s2, 0x90
	v_writelane_b32 v255, s5, 15
	v_cmp_gt_u32_e64 s[4:5], s1, v32
	v_add_u32_e32 v32, 0xffffff7f, v137
	v_or_b32_e32 v153, 16, v103
	v_writelane_b32 v255, s4, 16
	v_subrev_u32_e32 v44, 17, v42
	v_mul_lo_u32 v3, v81, s2
	v_writelane_b32 v255, s5, 17
	v_cmp_lt_u32_e64 s[4:5], s0, v137
	v_mul_lo_u32 v36, v148, s2
	v_mul_lo_u32 v39, v150, s2
	v_writelane_b32 v255, s4, 18
	v_mad_u32_u24 v154, v153, s2, 0
	v_cmp_gt_u32_e64 s[2:3], s1, v44
	v_writelane_b32 v255, s5, 19
	v_cmp_gt_u32_e64 s[4:5], s1, v33
	v_add_u32_e32 v43, -16, v42
	v_subrev_u32_e32 v44, 19, v42
	v_writelane_b32 v255, s4, 20
	v_lshlrev_b32_e32 v1, 4, v76
	v_cvt_f32_ubyte0_e32 v155, v42
	v_writelane_b32 v255, s5, 21
	v_cmp_gt_u32_e64 s[4:5], s1, v32
	v_add_u32_e32 v32, 0xffffff7d, v137
	v_and_b32_e32 v1, 0x70, v1
	v_writelane_b32 v255, s4, 22
	v_add_u32_e32 v1, 0, v1
	v_add_u32_e32 v29, 0, v29
	v_writelane_b32 v255, s5, 23
	v_cmp_gt_u32_e64 s[4:5], s1, v32
	v_lshlrev_b32_e32 v151, 3, v34
	v_add_u32_e32 v35, 0, v35
	v_writelane_b32 v255, s4, 24
	v_lshlrev_b32_e32 v34, 4, v34
	v_add_u32_e32 v32, 0x900, v154
	v_writelane_b32 v255, s5, 25
	v_writelane_b32 v255, s2, 26
	v_add_u32_e32 v33, 0x1200, v154
	v_add_u32_e32 v41, 0x3f00, v154
	v_writelane_b32 v255, s3, 27
	v_cmp_gt_u32_e64 s[2:3], s1, v43
	v_subrev_u32_e32 v43, 18, v42
	v_cvt_f32_ubyte0_e32 v152, v137
	v_writelane_b32 v255, s2, 28
	v_add_u32_e32 v156, v1, v3
	v_add_u32_e32 v157, v29, v31
	v_writelane_b32 v255, s3, 29
	v_cmp_gt_u32_e64 s[2:3], s1, v44
	v_add_u32_e32 v44, 0xffffff6f, v42
	v_add_u32_e32 v158, v1, v36
	v_writelane_b32 v255, s2, 30
	v_add_u32_e32 v159, v37, v38
	v_add_u32_e32 v161, v1, v39
	v_writelane_b32 v255, s3, 31
	v_cmp_gt_u32_e64 s[2:3], s1, v43
	v_add_u32_e32 v43, 0xffffff70, v42
	v_add_u32_e32 v166, v35, v34
	v_writelane_b32 v255, s2, 32
	v_lshlrev_b32_e32 v88, 1, v0
	v_lshlrev_b32_e32 v90, 1, v28
	v_writelane_b32 v255, s3, 33
	v_cmp_gt_u32_e64 s[2:3], s1, v44
	v_lshlrev_b32_e32 v92, 1, v30
	v_add_u32_e32 v167, v32, v80
	v_writelane_b32 v255, s2, 34
	v_add_u32_e32 v168, v33, v80
	v_add_u32_e32 v169, v41, v80
	v_writelane_b32 v255, s3, 35
	v_cmp_gt_u32_e64 s[2:3], s1, v43
	v_add_u32_e32 v43, 0xffffff6e, v42
	v_add_u32_e32 v42, 0xffffff6d, v42
	v_writelane_b32 v255, s2, 36
	v_add_u32_e32 v170, v79, v80
	v_add_u32_e32 v171, v40, v77
	v_writelane_b32 v255, s3, 37
	v_cmp_gt_u32_e64 s[2:3], s1, v43
	v_cmp_gt_u32_e64 s[0:1], s1, v42
	s_mov_b32 s6, s51
	v_writelane_b32 v255, s2, 38
	s_nop 1
	v_writelane_b32 v255, s3, 39
	v_writelane_b32 v255, s0, 40
	s_nop 1
	v_writelane_b32 v255, s1, 41
	s_mov_b32 s99, 1
	s_branch .LBB0_548

.LBB0_548:
	s_mul_hi_i32 s0, s6, 0x7e07e07f
	s_lshr_b32 s1, s0, 31
	s_ashr_i32 s0, s0, 8
	s_add_i32 s0, s0, s1
	s_mul_i32 s1, s0, 0xfffffdf8
	s_add_i32 s7, s6, s1
	s_mul_hi_i32 s1, s7, 0x7e07e07f
	s_lshr_b32 s4, s1, 31
	s_ashr_i32 s1, s1, 5
	s_add_i32 s1, s1, s4
	s_mul_i32 s4, s1, 0xffffffbf
	s_add_i32 s4, s7, s4
	s_lshl_b32 s70, s4, 5
	s_mulk_i32 s0, 0x810
	s_lshl_b32 s5, s1, 3
	s_add_i32 s60, s70, s0
	s_add_i32 s5, s5, s68
	v_or_b32_e32 v0, s60, v103
	s_lshl_b32 s44, s5, 6
	s_ashr_i32 s45, s44, 31
	v_ashrrev_i32_e32 v1, 31, v0
	s_lshl_b64 s[0:1], s[44:45], 1
	v_lshlrev_b64 v[112:113], 13, v[0:1]
	v_add_u32_e32 v0, 16, v0
	v_lshl_add_u64 v[28:29], v[82:83], 0, s[0:1]
	v_ashrrev_i32_e32 v1, 31, v0
	v_lshl_add_u64 v[40:41], v[84:85], 0, s[0:1]
	v_lshl_add_u64 v[30:31], v[28:29], 0, v[112:113]
	v_lshlrev_b64 v[0:1], 13, v[0:1]
	s_cmp_eq_u32 s99, 0
	s_cbranch_scc1 .Lattn_pf_hit
	global_load_dwordx4 v[36:39], v[30:31], off
	global_load_dwordx4 v[72:75], v[30:31], off offset:64
	v_lshl_add_u64 v[30:31], v[40:41], 0, v[112:113]
	v_lshl_add_u64 v[28:29], v[28:29], 0, v[0:1]
	v_lshl_add_u64 v[0:1], v[40:41], 0, v[0:1]
	global_load_dwordx2 v[110:111], v[30:31], off
	global_load_dwordx2 v[108:109], v[30:31], off offset:32
	global_load_dwordx2 v[106:107], v[30:31], off offset:64
	global_load_dwordx2 v[104:105], v[30:31], off offset:96
	global_load_dwordx4 v[32:35], v[28:29], off
	s_nop 0
	global_load_dwordx4 v[28:31], v[28:29], off offset:64
	s_nop 0
	global_load_dwordx2 v[100:101], v[0:1], off
	global_load_dwordx2 v[98:99], v[0:1], off offset:32
	global_load_dwordx2 v[96:97], v[0:1], off offset:64
	global_load_dwordx2 v[94:95], v[0:1], off offset:96
	s_mov_b32 s99, 0
	s_waitcnt vmcnt(0)
	s_branch .Lattn_pf_done
.Lattn_pf_hit:
	s_waitcnt vmcnt(8)
	v_mov_b64_e32 v[36:37], v[188:189]
	v_mov_b64_e32 v[38:39], v[190:191]
	v_mov_b64_e32 v[72:73], v[192:193]
	v_mov_b64_e32 v[74:75], v[194:195]
	v_mov_b64_e32 v[32:33], v[196:197]
	v_mov_b64_e32 v[34:35], v[198:199]
	v_mov_b64_e32 v[28:29], v[200:201]
	v_mov_b64_e32 v[30:31], v[202:203]
	v_mov_b64_e32 v[110:111], v[216:217]
	v_mov_b64_e32 v[108:109], v[218:219]
	v_mov_b64_e32 v[106:107], v[220:221]
	v_mov_b64_e32 v[104:105], v[222:223]
	v_mov_b64_e32 v[100:101], v[224:225]
	v_mov_b64_e32 v[98:99], v[226:227]
	v_mov_b64_e32 v[96:97], v[228:229]
	v_mov_b64_e32 v[94:95], v[230:231]
.Lattn_pf_done:
	s_mul_i32 s0, s7, 0xfc1
	s_lshr_b32 s1, s0, 31
	s_ashr_i32 s0, s0, 18
	s_add_i32 s0, s0, s1
	s_mulk_i32 s0, 0x41
	s_sub_i32 s0, s7, s0
	s_waitcnt lgkmcnt(0)
	s_barrier
	s_sext_i32_i16 s0, s0
	s_lshl_b32 s0, s0, 5
	v_readlane_b32 s2, v255, 3
	s_sub_i32 s7, 0x7f, s0
	v_readlane_b32 s3, v255, 4
	s_and_saveexec_b64 s[0:1], s[2:3]
	s_cbranch_execz .LBB0_550
	v_cmp_lt_i32_e32 vcc, s7, v81
	s_nop 0
	s_nop 0
	v_cndmask_b32_e32 v7, 0, v7, vcc
	v_cndmask_b32_e32 v6, 0, v6, vcc
	v_cndmask_b32_e32 v5, 0, v5, vcc
	v_cndmask_b32_e32 v4, 0, v4, vcc
	v_cmp_lt_i32_e32 vcc, s7, v147
	ds_write_b128 v156, v[4:7]
	s_nop 0
	v_cndmask_b32_e32 v7, 0, v11, vcc
	v_cndmask_b32_e32 v6, 0, v10, vcc
	v_cndmask_b32_e32 v5, 0, v9, vcc
	v_cndmask_b32_e32 v4, 0, v8, vcc
	ds_write_b128 v157, v[4:7] offset:23040
.LBB0_550:
	s_or_b64 exec, exec, s[0:1]
	v_readlane_b32 s2, v255, 5
	v_readlane_b32 s3, v255, 6
	s_and_saveexec_b64 s[0:1], s[2:3]
	s_cbranch_execz .LBB0_552
	v_cmp_lt_i32_e32 vcc, s7, v148
	s_nop 0
	s_nop 0
	v_cndmask_b32_e32 v7, 0, v15, vcc
	v_cndmask_b32_e32 v6, 0, v14, vcc
	v_cndmask_b32_e32 v5, 0, v13, vcc
	v_cndmask_b32_e32 v4, 0, v12, vcc
	v_cmp_lt_i32_e32 vcc, s7, v149
	ds_write_b128 v158, v[4:7]
	s_nop 0
	v_cndmask_b32_e32 v7, 0, v19, vcc
	v_cndmask_b32_e32 v6, 0, v18, vcc
	v_cndmask_b32_e32 v5, 0, v17, vcc
	v_cndmask_b32_e32 v4, 0, v16, vcc
	ds_write_b128 v159, v[4:7] offset:23040
.LBB0_552:
	s_or_b64 exec, exec, s[0:1]
	v_readlane_b32 s2, v255, 7
	v_readlane_b32 s3, v255, 8
	s_and_saveexec_b64 s[0:1], s[2:3]
	s_cbranch_execz .LBB0_554
	v_cmp_lt_i32_e32 vcc, s7, v150
	s_nop 0
	s_nop 0
	v_cndmask_b32_e32 v7, 0, v23, vcc
	v_cndmask_b32_e32 v6, 0, v22, vcc
	v_cndmask_b32_e32 v5, 0, v21, vcc
	v_cndmask_b32_e32 v4, 0, v20, vcc
	v_cmp_lt_i32_e32 vcc, s7, v151
	ds_write_b128 v161, v[4:7]
	s_nop 0
	v_cndmask_b32_e32 v7, 0, v27, vcc
	v_cndmask_b32_e32 v6, 0, v26, vcc
	v_cndmask_b32_e32 v5, 0, v25, vcc
	v_cndmask_b32_e32 v4, 0, v24, vcc
	ds_write_b128 v166, v[4:7] offset:23040
.LBB0_554:
	s_or_b64 exec, exec, s[0:1]
	s_add_i32 s46, s6, s92
	s_cmpk_gt_i32 s46, 0x81f
	s_cselect_b64 s[2:3], -1, 0
	s_cmpk_lt_i32 s46, 0x820
	s_cselect_b32 s0, s46, s6
	s_mul_hi_i32 s1, s0, 0x7e07e07f
	s_lshr_b32 s6, s1, 31
	s_ashr_i32 s1, s1, 8
	s_add_i32 s1, s1, s6
	s_mul_i32 s6, s1, 0xfffffdf8
	s_add_i32 s6, s6, s0
	s_mul_hi_i32 s0, s6, 0x7e07e07f
	s_lshr_b32 s7, s0, 31
	s_ashr_i32 s0, s0, 5
	s_add_i32 s7, s0, s7
	s_mul_i32 s0, s7, 0xffffffbf
	s_add_i32 s0, s0, s6
	s_lshl_b32 s0, s0, 5
	s_add_i32 s12, s0, 0xffffff80
	s_lshl_b32 s6, s7, 6
	v_add_u32_e32 v0, s12, v138
	s_mul_i32 s0, s1, 0x810
	s_ashr_i32 s7, s6, 31
	v_max_i32_e32 v0, 0, v0
	s_lshl_b64 s[8:9], s[6:7], 1
	s_add_i32 s100, s0, s12
	s_addk_i32 s100, 0x80
	s_lshl_b32 s101, s6, 3
	s_lshl_b32 s98, s68, 6
	s_add_i32 s101, s101, s98
	s_lshl_b32 s101, s101, 1
	v_readlane_b32 s10, v252, 25
	v_add_u32_e32 v0, s0, v0
	v_readlane_b32 s11, v252, 26
	s_add_u32 s8, s10, s8
	v_ashrrev_i32_e32 v1, 31, v0
	s_addc_u32 s9, s11, s9
	v_lshlrev_b64 v[0:1], 10, v[0:1]
	v_lshl_add_u64 v[0:1], s[8:9], 0, v[0:1]
	v_mov_b32_e32 v89, v2
	v_lshl_add_u64 v[0:1], v[0:1], 0, v[88:89]
	global_load_dwordx4 v[4:7], v[0:1], off
	v_add_u32_e32 v0, s12, v140
	v_max_i32_e32 v3, 0, v0
	s_nop 0
	v_lshlrev_b32_e32 v10, 1, v3
	v_add_u32_e32 v3, s12, v141
	v_max_i32_e32 v3, 0, v3
	s_nop 0
	v_add_u32_e32 v12, s0, v3
	v_add_u32_e32 v3, s12, v143
	s_ashr_i32 s1, s0, 31
	v_max_i32_e32 v3, 0, v3
	s_lshl_b64 s[10:11], s[0:1], 1
	v_readlane_b32 s14, v252, 31
	s_nop 0
	v_lshlrev_b32_e32 v18, 1, v3
	v_add_u32_e32 v3, s12, v144
	v_readlane_b32 s15, v252, 32
	s_add_u32 s10, s14, s10
	v_max_i32_e32 v3, 0, v3
	s_addc_u32 s11, s15, s11
	s_nop 0
	v_add_u32_e32 v20, s0, v3
	v_add_u32_e32 v3, s12, v146
	v_add_u32_e32 v8, s6, v139
	v_mov_b64_e32 v[0:1], s[10:11]
	v_add_u32_e32 v16, s6, v142
	v_max_i32_e32 v3, 0, v3
	s_nop 0
	v_add_u32_e32 v24, s6, v145
	v_mad_i64_i32 v[8:9], s[10:11], v8, s93, v[0:1]
	v_mov_b32_e32 v11, v2
	v_mad_i64_i32 v[16:17], s[10:11], v16, s93, v[0:1]
	v_mad_i64_i32 v[0:1], s[0:1], v24, s93, v[0:1]
	v_lshlrev_b32_e32 v24, 1, v3
	v_mov_b32_e32 v25, v2
	v_lshl_add_u64 v[8:9], v[8:9], 0, v[10:11]
	v_lshl_add_u64 v[0:1], v[0:1], 0, v[24:25]
	s_add_i32 s0, s5, 1
	global_load_dwordx4 v[8:11], v[8:9], off
	v_ashrrev_i32_e32 v13, 31, v12
	global_load_dwordx4 v[24:27], v[0:1], off
	v_cvt_f32_i32_e32 v0, s0
	v_ashrrev_i32_e32 v21, 31, v20
	v_lshlrev_b64 v[12:13], 10, v[12:13]
	v_lshlrev_b64 v[20:21], 10, v[20:21]
	v_mul_f32_e32 v1, 0xbe000000, v0
	v_cmp_gt_f32_e32 vcc, s94, v1
	s_and_b64 s[0:1], vcc, exec
	s_cselect_b32 s0, 0xffffffc0, 0
	v_cndmask_b32_e32 v1, 0, v213, vcc
	v_fmac_f32_e32 v1, 0xbe000000, v0
	v_exp_f32_e32 v0, v1
	v_lshl_add_u64 v[12:13], s[8:9], 0, v[12:13]
	v_lshl_add_u64 v[20:21], s[8:9], 0, v[20:21]
	v_readlane_b32 s8, v251, 4
	v_ldexp_f32 v0, v0, s0
	v_readlane_b32 s0, v255, 9
	s_add_i32 s0, s5, s0
	s_ashr_i32 s1, s0, 31
	v_mov_b32_e32 v91, v2
	v_mov_b32_e32 v19, v2
	v_mov_b32_e32 v93, v2
	s_lshl_b64 s[0:1], s[0:1], 2
	v_readlane_b32 s22, v251, 18
	v_lshl_add_u64 v[12:13], v[12:13], 0, v[90:91]
	v_lshl_add_u64 v[16:17], v[16:17], 0, v[18:19]
	v_lshl_add_u64 v[20:21], v[20:21], 0, v[92:93]
	v_readlane_b32 s23, v251, 19
	s_add_u32 s0, s22, s0
	global_load_dwordx4 v[12:15], v[12:13], off
	s_addc_u32 s1, s23, s1
	global_load_dwordx4 v[16:19], v[16:17], off
	v_mul_f32_e32 v102, 0x3fb8aa3b, v0
	global_load_dwordx4 v[20:23], v[20:21], off
	v_or_b32_e32 v180, s100, v103
	v_mov_b32_e32 v181, 0
	v_lshlrev_b64 v[180:181], 13, v[180:181]
	v_or_b32_e32 v180, s101, v180
	v_lshl_add_u64 v[182:183], v[82:83], 0, v[180:181]
	v_lshl_add_u64 v[184:185], v[84:85], 0, v[180:181]
	global_load_dwordx4 v[188:191], v[182:183], off
	global_load_dwordx4 v[192:195], v[182:183], off offset:64
	global_load_dwordx2 v[216:217], v[184:185], off
	global_load_dwordx2 v[218:219], v[184:185], off offset:32
	global_load_dwordx2 v[220:221], v[184:185], off offset:64
	global_load_dwordx2 v[222:223], v[184:185], off offset:96
	v_mov_b32_e32 v186, 0x20000
	v_mov_b32_e32 v187, 0
	v_lshl_add_u64 v[182:183], v[182:183], 0, v[186:187]
	v_lshl_add_u64 v[184:185], v[184:185], 0, v[186:187]
	global_load_dwordx4 v[196:199], v[182:183], off
	global_load_dwordx4 v[200:203], v[182:183], off offset:64
	global_load_dwordx2 v[224:225], v[184:185], off
	global_load_dwordx2 v[226:227], v[184:185], off offset:32
	global_load_dwordx2 v[228:229], v[184:185], off offset:64
	global_load_dwordx2 v[230:231], v[184:185], off offset:96
	s_waitcnt lgkmcnt(0)
	s_barrier
	s_load_dword s98, s[0:1], 0x0
	ds_read_b128 v[40:43], v170
	ds_read_b128 v[44:47], v170 offset:64
	s_waitcnt lgkmcnt(1)
	v_mfma_f32_16x16x32_bf16 v[40:43], v[40:43], v[36:39], 0
	v_or_b32_e32 v0, s70, v78
	s_cmp_lt_i32 s4, 4
	s_mov_b32 s50, s92
	s_waitcnt lgkmcnt(0)
	v_mfma_f32_16x16x32_bf16 v[48:51], v[44:47], v[72:75], v[40:43]
	s_nop 2
	ds_read_b128 v[40:43], v170 offset:2304
	ds_read_b128 v[44:47], v170 offset:2368
	v_readlane_b32 s9, v251, 5
	v_readlane_b32 s10, v251, 6
	s_waitcnt lgkmcnt(1)
	v_mfma_f32_16x16x32_bf16 v[40:43], v[40:43], v[36:39], 0
	v_readlane_b32 s11, v251, 7
	v_readlane_b32 s12, v251, 8
	v_readlane_b32 s13, v251, 9
	s_waitcnt lgkmcnt(0)
	v_mfma_f32_16x16x32_bf16 v[68:71], v[44:47], v[72:75], v[40:43]
	v_readlane_b32 s14, v251, 10
	v_readlane_b32 s15, v251, 11
	v_readlane_b32 s16, v251, 12
	v_readlane_b32 s17, v251, 13
	v_readlane_b32 s18, v251, 14
	v_readlane_b32 s19, v251, 15
	v_readlane_b32 s20, v251, 16
	v_readlane_b32 s21, v251, 17
	v_sub_u32_e32 v172, 0x80, v0
	s_cselect_b64 s[54:55], -1, 0
	ds_read_b128 v[40:43], v170 offset:4608
	ds_read_b128 v[44:47], v170 offset:4672
	s_waitcnt lgkmcnt(1)
	v_mfma_f32_16x16x32_bf16 v[40:43], v[40:43], v[36:39], 0
	s_waitcnt lgkmcnt(0)
	v_mfma_f32_16x16x32_bf16 v[64:67], v[44:47], v[72:75], v[40:43]
	s_nop 5
	ds_read_b128 v[40:43], v170 offset:6912
	ds_read_b128 v[44:47], v170 offset:6976
	s_waitcnt lgkmcnt(1)
	v_mfma_f32_16x16x32_bf16 v[40:43], v[40:43], v[36:39], 0
	s_waitcnt lgkmcnt(0)
	v_mfma_f32_16x16x32_bf16 v[60:63], v[44:47], v[72:75], v[40:43]
	s_nop 5
	ds_read_b128 v[40:43], v170 offset:9216
	ds_read_b128 v[44:47], v170 offset:9280
	s_waitcnt lgkmcnt(1)
	v_mfma_f32_16x16x32_bf16 v[40:43], v[40:43], v[36:39], 0
	s_waitcnt lgkmcnt(0)
	v_mfma_f32_16x16x32_bf16 v[56:59], v[44:47], v[72:75], v[40:43]
	s_nop 5
	ds_read_b128 v[40:43], v170 offset:11520
	ds_read_b128 v[44:47], v170 offset:11584
	s_waitcnt lgkmcnt(1)
	v_mfma_f32_16x16x32_bf16 v[40:43], v[40:43], v[36:39], 0
	s_waitcnt lgkmcnt(0)
	v_mfma_f32_16x16x32_bf16 v[52:55], v[44:47], v[72:75], v[40:43]
	s_nop 5
	ds_read_b128 v[40:43], v170 offset:13824
	ds_read_b128 v[44:47], v170 offset:13888
	s_waitcnt lgkmcnt(1)
	v_mfma_f32_16x16x32_bf16 v[40:43], v[40:43], v[36:39], 0
	s_waitcnt lgkmcnt(0)
	v_mfma_f32_16x16x32_bf16 v[44:47], v[44:47], v[72:75], v[40:43]
	s_nop 5
	ds_read_b128 v[40:43], v170 offset:16128
	ds_read_b128 v[114:117], v170 offset:16192
	s_waitcnt lgkmcnt(1)
	v_mfma_f32_16x16x32_bf16 v[40:43], v[40:43], v[36:39], 0
	s_waitcnt lgkmcnt(0)
	v_mfma_f32_16x16x32_bf16 v[40:43], v[114:117], v[72:75], v[40:43]
	ds_read_b128 v[114:117], v170 offset:18432
	ds_read_b128 v[118:121], v170 offset:18496
	s_movk_i32 s56, 0x63
	v_cmp_gt_i32_e64 s[92:93], s56, v172
	s_movk_i32 s56, 0x64
	s_waitcnt lgkmcnt(1)
	v_mfma_f32_16x16x32_bf16 v[36:39], v[114:117], v[36:39], 0
	v_cmp_gt_i32_e64 s[94:95], s56, v172
	s_movk_i32 s56, 0x71
	s_movk_i32 s4, 0x41
	v_cmp_gt_i32_e64 s[88:89], s56, v172
	s_movk_i32 s56, 0x72
	v_cmp_gt_i32_e64 s[16:17], s4, v172
	s_movk_i32 s4, 0x42
	v_cmp_gt_i32_e64 s[90:91], s56, v172
	s_movk_i32 s56, 0x73
	v_cmp_gt_i32_e64 s[18:19], s4, v172
	s_movk_i32 s4, 0x43
	v_cmp_gt_i32_e64 s[84:85], s56, v172
	s_movk_i32 s56, 0x74
	s_waitcnt lgkmcnt(0)
	v_mfma_f32_16x16x32_bf16 v[36:39], v[118:121], v[72:75], v[36:39]
	v_cmp_gt_i32_e64 s[12:13], s4, v172
	s_movk_i32 s4, 0x44
	v_cmp_gt_i32_e64 s[86:87], s56, v172
	s_movk_i32 s56, 0x81
	v_cmp_gt_i32_e64 s[14:15], s4, v172
	s_movk_i32 s4, 0x51
	v_cmp_gt_i32_e64 s[82:83], s56, v172
	s_movk_i32 s56, 0x83
	v_cmp_gt_i32_e64 s[8:9], s4, v172
	s_movk_i32 s4, 0x52
	s_movk_i32 s42, 0x61
	v_cmp_gt_i32_e64 s[80:81], s56, v172
	s_movk_i32 s56, 0x82
	v_mul_f32_e32 v0, v102, v152
	v_cmp_gt_i32_e64 s[10:11], s4, v172
	s_movk_i32 s4, 0x53
	s_movk_i32 s6, 0x54
	v_cmp_gt_i32_e64 s[96:97], s42, v172
	s_movk_i32 s42, 0x62
	v_cmp_gt_i32_e64 s[78:79], s56, v172
	s_movk_i32 s56, 0x84
	s_mov_b64 s[58:59], -1
	s_and_b64 vcc, exec, s[54:55]
	v_cmp_gt_i32_e64 s[38:39], 17, v172
	v_cmp_gt_i32_e64 s[40:41], 18, v172
	v_cmp_gt_i32_e64 s[36:37], 19, v172
	v_cmp_gt_i32_e64 s[52:53], 20, v172
	v_cmp_gt_i32_e64 s[34:35], 33, v172
	v_cmp_gt_i32_e64 s[0:1], 34, v172
	v_cmp_gt_i32_e64 s[26:27], 35, v172
	v_cmp_gt_i32_e64 s[30:31], 36, v172
	v_cmp_gt_i32_e64 s[24:25], 49, v172
	v_cmp_gt_i32_e64 s[28:29], 50, v172
	v_cmp_gt_i32_e64 s[20:21], 51, v172
	v_cmp_gt_i32_e64 s[22:23], 52, v172
	v_cmp_gt_i32_e64 s[4:5], s4, v172
	v_cmp_gt_i32_e64 s[6:7], s6, v172
	v_cmp_gt_i32_e64 s[42:43], s42, v172
	v_cmp_gt_i32_e64 s[76:77], s56, v172
	v_sub_f32_e32 v174, v48, v0
	v_sub_f32_e32 v173, v49, v0
	v_sub_f32_e32 v93, v36, v0
	s_cbranch_vccz .LBB0_556
	v_readlane_b32 s56, v255, 10
	v_cmp_gt_i32_e32 vcc, 1, v172
	v_readlane_b32 s57, v255, 11
	v_fma_f32 v3, 0, v102, v174
	s_and_b64 vcc, s[56:57], vcc
	v_readlane_b32 s56, v255, 12
	v_cndmask_b32_e32 v3, v214, v3, vcc
	v_cmp_gt_i32_e32 vcc, 2, v172
	v_readlane_b32 s57, v255, 13
	s_and_b64 vcc, s[56:57], vcc
	s_mov_b32 s56, 2.0
	s_nop 0
	v_pk_add_f32 v[48:49], v[50:51], v[0:1] op_sel_hi:[1,0] neg_lo:[0,1] neg_hi:[0,1]
	s_mov_b32 s57, 0x40400000
	v_add_f32_e32 v36, v102, v173
	v_pk_fma_f32 v[48:49], v[102:103], s[56:57], v[48:49] op_sel_hi:[0,1,1]
	v_readlane_b32 s56, v255, 14
	v_cndmask_b32_e32 v36, v214, v36, vcc
	v_cmp_gt_i32_e32 vcc, 4, v172
	v_readlane_b32 s57, v255, 15
	s_and_b64 vcc, s[56:57], vcc
	v_readlane_b32 s56, v255, 16
	v_cndmask_b32_e32 v89, v214, v49, vcc
	v_cmp_gt_i32_e32 vcc, 3, v172
	v_readlane_b32 s57, v255, 17
	s_and_b64 vcc, s[56:57], vcc
	s_mov_b32 s56, 0x41800000
	v_cndmask_b32_e32 v91, v214, v48, vcc
	v_pk_add_f32 v[48:49], v[68:69], v[0:1] op_sel_hi:[1,0] neg_lo:[0,1] neg_hi:[0,1]
	s_mov_b32 s57, 0x41880000
	v_pk_fma_f32 v[48:49], v[102:103], s[56:57], v[48:49] op_sel_hi:[0,1,1]
	v_cndmask_b32_e64 v48, v214, v48, s[38:39]
	s_mov_b32 s38, 0x41900000
	v_pk_add_f32 v[72:73], v[70:71], v[0:1] op_sel_hi:[1,0] neg_lo:[0,1] neg_hi:[0,1]
	s_mov_b32 s39, 0x41980000
	v_pk_fma_f32 v[72:73], v[102:103], s[38:39], v[72:73] op_sel_hi:[0,1,1]
	v_cndmask_b32_e64 v72, v214, v72, s[36:37]
	s_mov_b32 s36, 0x42000000
	v_pk_add_f32 v[74:75], v[64:65], v[0:1] op_sel_hi:[1,0] neg_lo:[0,1] neg_hi:[0,1]
	s_mov_b32 s37, 0x42040000
	v_pk_fma_f32 v[74:75], v[102:103], s[36:37], v[74:75] op_sel_hi:[0,1,1]
	v_cndmask_b32_e64 v75, v214, v75, s[0:1]
	s_mov_b32 s0, 0x42080000
	v_max_f32_e32 v118, 0xf149f2ca, v3
	v_pk_add_f32 v[114:115], v[66:67], v[0:1] op_sel_hi:[1,0] neg_lo:[0,1] neg_hi:[0,1]
	s_mov_b32 s1, 0x420c0000
	v_max3_f32 v118, v118, v36, v91
	v_cndmask_b32_e64 v49, v214, v49, s[40:41]
	v_pk_fma_f32 v[114:115], v[102:103], s[0:1], v[114:115] op_sel_hi:[0,1,1]
	s_mov_b32 s0, 0x42400000
	v_max3_f32 v118, v118, v89, v48
	v_cndmask_b32_e64 v73, v214, v73, s[52:53]
	v_cndmask_b32_e64 v74, v214, v74, s[34:35]
	v_pk_add_f32 v[116:117], v[60:61], v[0:1] op_sel_hi:[1,0] neg_lo:[0,1] neg_hi:[0,1]
	s_mov_b32 s1, 0x42440000
	v_max3_f32 v118, v118, v49, v72
	v_cndmask_b32_e64 v114, v214, v114, s[26:27]
	v_pk_fma_f32 v[116:117], v[102:103], s[0:1], v[116:117] op_sel_hi:[0,1,1]
	v_max3_f32 v118, v118, v73, v74
	v_cndmask_b32_e64 v115, v214, v115, s[30:31]
	v_max3_f32 v118, v118, v75, v114
	v_cndmask_b32_e64 v116, v214, v116, s[24:25]
	s_mov_b32 s0, 0x42480000
	v_max3_f32 v120, v118, v115, v116
	v_pk_add_f32 v[118:119], v[62:63], v[0:1] op_sel_hi:[1,0] neg_lo:[0,1] neg_hi:[0,1]
	s_mov_b32 s1, 0x424c0000
	v_pk_fma_f32 v[118:119], v[102:103], s[0:1], v[118:119] op_sel_hi:[0,1,1]
	v_cndmask_b32_e64 v117, v214, v117, s[28:29]
	v_cndmask_b32_e64 v118, v214, v118, s[20:21]
	s_mov_b32 s0, 0x42800000
	v_max3_f32 v122, v120, v117, v118
	v_pk_add_f32 v[120:121], v[56:57], v[0:1] op_sel_hi:[1,0] neg_lo:[0,1] neg_hi:[0,1]
	s_mov_b32 s1, 0x42820000
	v_pk_fma_f32 v[120:121], v[102:103], s[0:1], v[120:121] op_sel_hi:[0,1,1]
	v_cndmask_b32_e64 v119, v214, v119, s[22:23]
	v_cndmask_b32_e64 v120, v214, v120, s[16:17]
	s_mov_b32 s0, 0x42840000
	v_max3_f32 v124, v122, v119, v120
	v_pk_add_f32 v[122:123], v[58:59], v[0:1] op_sel_hi:[1,0] neg_lo:[0,1] neg_hi:[0,1]
	s_mov_b32 s1, 0x42860000
	v_pk_fma_f32 v[122:123], v[102:103], s[0:1], v[122:123] op_sel_hi:[0,1,1]
	v_cndmask_b32_e64 v121, v214, v121, s[18:19]
	v_cndmask_b32_e64 v122, v214, v122, s[12:13]
	s_mov_b32 s0, 0x42a00000
	v_max3_f32 v126, v124, v121, v122
	v_pk_add_f32 v[124:125], v[52:53], v[0:1] op_sel_hi:[1,0] neg_lo:[0,1] neg_hi:[0,1]
	s_mov_b32 s1, 0x42a20000
	v_pk_fma_f32 v[124:125], v[102:103], s[0:1], v[124:125] op_sel_hi:[0,1,1]
	v_cndmask_b32_e64 v123, v214, v123, s[14:15]
	v_cndmask_b32_e64 v124, v214, v124, s[8:9]
	s_mov_b32 s0, 0x42a40000
	v_max3_f32 v128, v126, v123, v124
	v_pk_add_f32 v[126:127], v[54:55], v[0:1] op_sel_hi:[1,0] neg_lo:[0,1] neg_hi:[0,1]
	s_mov_b32 s1, 0x42a60000
	v_pk_fma_f32 v[126:127], v[102:103], s[0:1], v[126:127] op_sel_hi:[0,1,1]
	v_cndmask_b32_e64 v125, v214, v125, s[10:11]
	v_cndmask_b32_e64 v126, v214, v126, s[4:5]
	s_mov_b32 s0, 0x42c00000
	v_max3_f32 v130, v128, v125, v126
	v_pk_add_f32 v[128:129], v[44:45], v[0:1] op_sel_hi:[1,0] neg_lo:[0,1] neg_hi:[0,1]
	s_mov_b32 s1, 0x42c20000
	v_pk_fma_f32 v[128:129], v[102:103], s[0:1], v[128:129] op_sel_hi:[0,1,1]
	v_cndmask_b32_e64 v127, v214, v127, s[6:7]
	v_cndmask_b32_e64 v128, v214, v128, s[96:97]
	s_mov_b32 s0, 0x42c40000
	v_max3_f32 v132, v130, v127, v128
	v_pk_add_f32 v[130:131], v[46:47], v[0:1] op_sel_hi:[1,0] neg_lo:[0,1] neg_hi:[0,1]
	s_mov_b32 s1, 0x42c60000
	v_pk_fma_f32 v[130:131], v[102:103], s[0:1], v[130:131] op_sel_hi:[0,1,1]
	v_cndmask_b32_e64 v129, v214, v129, s[42:43]
	v_cndmask_b32_e64 v130, v214, v130, s[92:93]
	s_mov_b32 s0, 0x42e00000
	v_max3_f32 v134, v132, v129, v130
	v_pk_add_f32 v[132:133], v[40:41], v[0:1] op_sel_hi:[1,0] neg_lo:[0,1] neg_hi:[0,1]
	s_mov_b32 s1, 0x42e20000
	v_pk_fma_f32 v[132:133], v[102:103], s[0:1], v[132:133] op_sel_hi:[0,1,1]
	v_cndmask_b32_e64 v131, v214, v131, s[94:95]
	v_cndmask_b32_e64 v132, v214, v132, s[88:89]
	s_mov_b32 s0, 0x42e40000
	v_max3_f32 v162, v134, v131, v132
	v_pk_add_f32 v[134:135], v[42:43], v[0:1] op_sel_hi:[1,0] neg_lo:[0,1] neg_hi:[0,1]
	s_mov_b32 s1, 0x42e60000
	v_pk_fma_f32 v[134:135], v[102:103], s[0:1], v[134:135] op_sel_hi:[0,1,1]
	v_readlane_b32 s0, v255, 18
	v_readlane_b32 s1, v255, 19
	v_cndmask_b32_e64 v133, v214, v133, s[90:91]
	v_cndmask_b32_e64 v134, v214, v134, s[84:85]
	v_fmamk_f32 v163, v102, 0x43000000, v93
	s_and_b64 vcc, s[0:1], s[82:83]
	v_cndmask_b32_e64 v135, v214, v135, s[86:87]
	v_max3_f32 v162, v162, v133, v134
	v_cndmask_b32_e32 v175, v214, v163, vcc
	v_max3_f32 v178, v162, v135, v175
	v_mov_b32_e32 v162, v37
	v_mov_b32_e32 v163, v38
	s_mov_b32 s0, 0x43010000
	v_pk_add_f32 v[162:163], v[162:163], v[0:1] op_sel_hi:[1,0] neg_lo:[0,1] neg_hi:[0,1]
	s_mov_b32 s1, 0x43020000
	v_pk_fma_f32 v[162:163], v[102:103], s[0:1], v[162:163] op_sel_hi:[0,1,1]
	v_readlane_b32 s0, v255, 20
	v_readlane_b32 s1, v255, 21
	s_and_b64 vcc, s[0:1], s[80:81]
	v_readlane_b32 s0, v255, 22
	v_readlane_b32 s1, v255, 23
	v_cndmask_b32_e32 v176, v214, v163, vcc
	s_and_b64 vcc, s[0:1], s[78:79]
	v_readlane_b32 s0, v255, 24
	v_cndmask_b32_e32 v177, v214, v162, vcc
	v_readlane_b32 s1, v255, 25
	v_max3_f32 v178, v178, v177, v176
	s_and_b64 s[56:57], s[0:1], s[76:77]
	s_mov_b64 s[58:59], 0
.LBB0_556:
	s_andn2_b64 vcc, exec, s[58:59]
	s_cbranch_vccnz .LBB0_558
	v_readlane_b32 s0, v255, 12
	v_add_f32_e32 v36, v102, v173
	v_readlane_b32 s1, v255, 13
	s_nop 0
	v_pk_add_f32 v[48:49], v[50:51], v[0:1] op_sel_hi:[1,0] neg_lo:[0,1] neg_hi:[0,1]
	v_readlane_b32 s4, v255, 10
	v_cndmask_b32_e64 v36, v214, v36, s[0:1]
	s_mov_b32 s0, 2.0
	s_mov_b32 s1, 0x40400000
	v_pk_fma_f32 v[48:49], v[102:103], s[0:1], v[48:49] op_sel_hi:[0,1,1]
	v_readlane_b32 s0, v255, 14
	v_readlane_b32 s1, v255, 15
	v_fmac_f32_e32 v174, 0, v102
	v_readlane_b32 s5, v255, 11
	v_cndmask_b32_e64 v89, v214, v49, s[0:1]
	v_readlane_b32 s0, v255, 16
	v_readlane_b32 s1, v255, 17
	v_cndmask_b32_e64 v3, v214, v174, s[4:5]
	v_max_f32_e32 v72, 0xf149f2ca, v3
	v_cndmask_b32_e64 v91, v214, v48, s[0:1]
	s_mov_b32 s0, 0x41800000
	v_pk_add_f32 v[48:49], v[68:69], v[0:1] op_sel_hi:[1,0] neg_lo:[0,1] neg_hi:[0,1]
	s_mov_b32 s1, 0x41880000
	v_max3_f32 v50, v72, v36, v91
	v_pk_fma_f32 v[48:49], v[102:103], s[0:1], v[48:49] op_sel_hi:[0,1,1]
	s_mov_b32 s0, 0x41900000
	v_max3_f32 v68, v50, v89, v48
	v_pk_add_f32 v[50:51], v[70:71], v[0:1] op_sel_hi:[1,0] neg_lo:[0,1] neg_hi:[0,1]
	s_mov_b32 s1, 0x41980000
	v_pk_fma_f32 v[72:73], v[102:103], s[0:1], v[50:51] op_sel_hi:[0,1,1]
	s_mov_b32 s0, 0x42000000
	v_pk_add_f32 v[50:51], v[64:65], v[0:1] op_sel_hi:[1,0] neg_lo:[0,1] neg_hi:[0,1]
	s_mov_b32 s1, 0x42040000
	v_pk_fma_f32 v[74:75], v[102:103], s[0:1], v[50:51] op_sel_hi:[0,1,1]
	s_mov_b32 s0, 0x42080000
	v_pk_add_f32 v[50:51], v[66:67], v[0:1] op_sel_hi:[1,0] neg_lo:[0,1] neg_hi:[0,1]
	s_mov_b32 s1, 0x420c0000
	v_pk_fma_f32 v[114:115], v[102:103], s[0:1], v[50:51] op_sel_hi:[0,1,1]
	s_mov_b32 s0, 0x42400000
	v_pk_add_f32 v[50:51], v[60:61], v[0:1] op_sel_hi:[1,0] neg_lo:[0,1] neg_hi:[0,1]
	s_mov_b32 s1, 0x42440000
	v_pk_fma_f32 v[116:117], v[102:103], s[0:1], v[50:51] op_sel_hi:[0,1,1]
	s_mov_b32 s0, 0x42480000
	v_pk_add_f32 v[50:51], v[62:63], v[0:1] op_sel_hi:[1,0] neg_lo:[0,1] neg_hi:[0,1]
	s_mov_b32 s1, 0x424c0000
	v_pk_fma_f32 v[118:119], v[102:103], s[0:1], v[50:51] op_sel_hi:[0,1,1]
	s_mov_b32 s0, 0x42800000
	v_pk_add_f32 v[50:51], v[56:57], v[0:1] op_sel_hi:[1,0] neg_lo:[0,1] neg_hi:[0,1]
	s_mov_b32 s1, 0x42820000
	v_pk_fma_f32 v[120:121], v[102:103], s[0:1], v[50:51] op_sel_hi:[0,1,1]
	s_mov_b32 s0, 0x42840000
	v_pk_add_f32 v[50:51], v[58:59], v[0:1] op_sel_hi:[1,0] neg_lo:[0,1] neg_hi:[0,1]
	s_mov_b32 s1, 0x42860000
	v_pk_fma_f32 v[122:123], v[102:103], s[0:1], v[50:51] op_sel_hi:[0,1,1]
	s_mov_b32 s0, 0x42a00000
	v_max3_f32 v68, v68, v49, v72
	v_pk_add_f32 v[50:51], v[52:53], v[0:1] op_sel_hi:[1,0] neg_lo:[0,1] neg_hi:[0,1]
	s_mov_b32 s1, 0x42a20000
	v_max3_f32 v64, v68, v73, v74
	v_pk_fma_f32 v[124:125], v[102:103], s[0:1], v[50:51] op_sel_hi:[0,1,1]
	s_mov_b32 s0, 0x42a40000
	v_max3_f32 v64, v64, v75, v114
	v_pk_add_f32 v[50:51], v[54:55], v[0:1] op_sel_hi:[1,0] neg_lo:[0,1] neg_hi:[0,1]
	s_mov_b32 s1, 0x42a60000
	v_max3_f32 v60, v64, v115, v116
	v_pk_fma_f32 v[126:127], v[102:103], s[0:1], v[50:51] op_sel_hi:[0,1,1]
	s_mov_b32 s0, 0x42c00000
	v_max3_f32 v60, v60, v117, v118
	v_pk_add_f32 v[44:45], v[44:45], v[0:1] op_sel_hi:[1,0] neg_lo:[0,1] neg_hi:[0,1]
	s_mov_b32 s1, 0x42c20000
	v_max3_f32 v56, v60, v119, v120
	v_pk_fma_f32 v[128:129], v[102:103], s[0:1], v[44:45] op_sel_hi:[0,1,1]
	s_mov_b32 s0, 0x42c40000
	v_max3_f32 v56, v56, v121, v122
	v_pk_add_f32 v[44:45], v[46:47], v[0:1] op_sel_hi:[1,0] neg_lo:[0,1] neg_hi:[0,1]
	s_mov_b32 s1, 0x42c60000
	v_max3_f32 v52, v56, v123, v124
	v_pk_fma_f32 v[130:131], v[102:103], s[0:1], v[44:45] op_sel_hi:[0,1,1]
	s_mov_b32 s0, 0x42e00000
	v_max3_f32 v50, v52, v125, v126
	v_pk_add_f32 v[40:41], v[40:41], v[0:1] op_sel_hi:[1,0] neg_lo:[0,1] neg_hi:[0,1]
	s_mov_b32 s1, 0x42e20000
	v_max3_f32 v50, v50, v127, v128
	v_pk_fma_f32 v[132:133], v[102:103], s[0:1], v[40:41] op_sel_hi:[0,1,1]
	s_mov_b32 s0, 0x42e40000
	v_max3_f32 v44, v50, v129, v130
	v_pk_add_f32 v[40:41], v[42:43], v[0:1] op_sel_hi:[1,0] neg_lo:[0,1] neg_hi:[0,1]
	s_mov_b32 s1, 0x42e60000
	v_max3_f32 v44, v44, v131, v132
	v_pk_fma_f32 v[134:135], v[102:103], s[0:1], v[40:41] op_sel_hi:[0,1,1]
	v_fmac_f32_e32 v93, 0x43000000, v102
	v_max3_f32 v40, v44, v133, v134
	v_cndmask_b32_e64 v175, v93, v214, s[4:5]
	v_max3_f32 v42, v40, v135, v175
	v_mov_b32_e32 v40, v37
	v_mov_b32_e32 v41, v38
	s_mov_b32 s0, 0x43010000
	v_pk_add_f32 v[40:41], v[40:41], v[0:1] op_sel_hi:[1,0] neg_lo:[0,1] neg_hi:[0,1]
	s_mov_b32 s1, 0x43020000
	v_pk_fma_f32 v[40:41], v[102:103], s[0:1], v[40:41] op_sel_hi:[0,1,1]
	v_readlane_b32 s0, v255, 20
	v_readlane_b32 s1, v255, 21
	v_readlane_b32 s4, v255, 24
	v_readlane_b32 s5, v255, 25
	v_cndmask_b32_e64 v176, v214, v41, s[0:1]
	v_readlane_b32 s0, v255, 22
	v_readlane_b32 s1, v255, 23
	s_and_b64 s[4:5], s[4:5], exec
	s_nop 0
	v_cndmask_b32_e64 v177, v214, v40, s[0:1]
	s_andn2_b64 s[0:1], s[56:57], exec
	v_max3_f32 v178, v42, v177, v176
	s_or_b64 s[56:57], s[0:1], s[4:5]
.LBB0_558:
	v_and_b32_e32 v38, 64, v208
	v_xor_b32_e32 v37, 16, v208
	v_add_u32_e32 v38, 64, v38
	v_cmp_lt_i32_e32 vcc, v37, v38
	v_sub_f32_e32 v0, v39, v0
	v_fmac_f32_e32 v0, 0x43030000, v102
	v_cndmask_b32_e32 v37, v208, v37, vcc
	v_lshlrev_b32_e32 v173, 2, v37
	v_cndmask_b32_e64 v0, v214, v0, s[56:57]
	v_max_f32_e32 v37, v178, v178
	v_max_f32_e32 v37, v37, v0
	ds_bpermute_b32 v39, v173, v37
	v_xor_b32_e32 v40, 32, v208
	v_cmp_lt_i32_e32 vcc, v40, v38
	v_mov_b32_e32 v67, 0x3fb8aa3b
	v_mul_f32_e32 v67, s98, v67
	v_add_u32_e32 v93, 0x5800, v171
	v_cndmask_b32_e32 v38, v208, v40, vcc
	v_lshlrev_b32_e32 v174, 2, v38
	s_waitcnt lgkmcnt(0)
	v_max_f32_e32 v38, v39, v39
	v_max_f32_e32 v37, v37, v38
	ds_bpermute_b32 v38, v174, v37
	s_mov_b32 s92, s50
	s_movk_i32 s93, 0x4400
	s_mov_b32 s94, 0xc2fc0000
	v_lshl_add_u64 v[64:65], s[44:45], 1, v[86:87]
	s_waitcnt lgkmcnt(0)
	v_max3_f32 v52, v37, v38, v67
	v_sub_f32_e32 v1, v3, v52
	v_exp_f32_e32 v1, v1
	v_sub_f32_e32 v3, v36, v52
	v_exp_f32_e32 v3, v3
	v_sub_f32_e32 v36, v91, v52
	v_exp_f32_e32 v41, v36
	v_sub_f32_e32 v37, v89, v52
	v_exp_f32_e32 v42, v37
	v_sub_f32_e32 v37, v48, v52
	v_add_f32_e32 v36, 0, v1
	v_exp_f32_e32 v43, v37
	v_sub_f32_e32 v37, v49, v52
	v_add_f32_e32 v36, v3, v36
	v_exp_f32_e32 v48, v37
	v_sub_f32_e32 v37, v72, v52
	v_add_f32_e32 v36, v41, v36
	v_exp_f32_e32 v49, v37
	v_sub_f32_e32 v37, v73, v52
	v_add_f32_e32 v36, v42, v36
	v_exp_f32_e32 v50, v37
	v_sub_f32_e32 v37, v74, v52
	v_add_f32_e32 v36, v43, v36
	v_exp_f32_e32 v55, v37
	v_sub_f32_e32 v37, v75, v52
	v_add_f32_e32 v36, v48, v36
	v_exp_f32_e32 v60, v37
	v_sub_f32_e32 v37, v114, v52
	v_add_f32_e32 v36, v49, v36
	v_exp_f32_e32 v61, v37
	v_sub_f32_e32 v37, v115, v52
	v_add_f32_e32 v36, v50, v36
	v_exp_f32_e32 v62, v37
	v_sub_f32_e32 v37, v116, v52
	v_add_f32_e32 v36, v55, v36
	v_exp_f32_e32 v63, v37
	v_sub_f32_e32 v37, v117, v52
	v_add_f32_e32 v36, v60, v36
	v_exp_f32_e32 v66, v37
	v_sub_f32_e32 v37, v118, v52
	v_add_f32_e32 v36, v61, v36
	v_exp_f32_e32 v68, v37
	v_sub_f32_e32 v37, v119, v52
	v_add_f32_e32 v36, v62, v36
	v_exp_f32_e32 v69, v37
	v_sub_f32_e32 v37, v120, v52
	v_add_f32_e32 v36, v63, v36
	v_exp_f32_e32 v70, v37
	v_sub_f32_e32 v37, v121, v52
	v_add_f32_e32 v36, v66, v36
	v_exp_f32_e32 v71, v37
	v_sub_f32_e32 v37, v122, v52
	v_add_f32_e32 v36, v68, v36
	v_exp_f32_e32 v72, v37
	v_sub_f32_e32 v37, v123, v52
	v_add_f32_e32 v36, v69, v36
	v_exp_f32_e32 v73, v37
	v_sub_f32_e32 v37, v124, v52
	v_add_f32_e32 v36, v70, v36
	v_exp_f32_e32 v74, v37
	v_sub_f32_e32 v37, v125, v52
	v_add_f32_e32 v36, v71, v36
	v_exp_f32_e32 v75, v37
	v_sub_f32_e32 v37, v126, v52
	v_add_f32_e32 v36, v72, v36
	v_exp_f32_e32 v114, v37
	v_sub_f32_e32 v37, v127, v52
	v_add_f32_e32 v36, v73, v36
	v_exp_f32_e32 v115, v37
	v_sub_f32_e32 v37, v128, v52
	v_add_f32_e32 v36, v74, v36
	v_exp_f32_e32 v116, v37
	v_sub_f32_e32 v37, v129, v52
	v_add_f32_e32 v36, v75, v36
	v_exp_f32_e32 v117, v37
	v_sub_f32_e32 v37, v130, v52
	v_add_f32_e32 v36, v114, v36
	v_exp_f32_e32 v118, v37
	v_sub_f32_e32 v37, v131, v52
	v_add_f32_e32 v36, v115, v36
	v_exp_f32_e32 v119, v37
	v_sub_f32_e32 v37, v132, v52
	v_add_f32_e32 v36, v116, v36
	v_exp_f32_e32 v120, v37
	v_sub_f32_e32 v37, v133, v52
	v_add_f32_e32 v36, v117, v36
	v_exp_f32_e32 v121, v37
	v_sub_f32_e32 v37, v134, v52
	v_add_f32_e32 v36, v118, v36
	v_exp_f32_e32 v122, v37
	v_sub_f32_e32 v37, v135, v52
	v_add_f32_e32 v36, v119, v36
	v_exp_f32_e32 v123, v37
	v_sub_f32_e32 v37, v175, v52
	v_add_f32_e32 v36, v120, v36
	v_exp_f32_e32 v125, v37
	v_sub_f32_e32 v37, v177, v52
	v_add_f32_e32 v36, v121, v36
	v_exp_f32_e32 v126, v37
	v_sub_f32_e32 v37, v176, v52
	v_add_f32_e32 v36, v122, v36
	v_exp_f32_e32 v127, v37
	v_sub_f32_e32 v0, v0, v52
	v_add_f32_e32 v36, v123, v36
	v_exp_f32_e32 v128, v0
	v_add_f32_e32 v36, v125, v36
	v_add_f32_e32 v36, v126, v36
	v_add_u32_e32 v124, 0x6800, v171
	v_add_u32_e32 v89, 0x8000, v171
	v_add_u32_e32 v91, 0x9800, v171
	v_add_f32_e32 v53, v127, v36
	ds_read2_b64 v[36:39], v93 offset0:64 offset1:68
	v_cvt_pk_bf16_f32 v41, v41, v42
	ds_read2_b64 v[44:47], v124 offset0:224 offset1:228
	v_cvt_pk_bf16_f32 v42, v43, v48
	v_cvt_pk_bf16_f32 v43, v49, v50
	ds_read2_b64 v[48:51], v89 offset0:128 offset1:132
	ds_read2_b64 v[56:59], v91 offset0:32 offset1:36
	v_add_f32_e32 v0, v128, v53
	v_cvt_pk_bf16_f32 v40, v1, v3
	ds_bpermute_b32 v1, v173, v0
	s_waitcnt lgkmcnt(0)
	v_add_f32_e32 v53, v0, v1
	ds_bpermute_b32 v54, v174, v53
	v_mfma_f32_16x16x32_bf16 v[36:39], v[36:39], v[40:43], 0
	v_mfma_f32_16x16x32_bf16 v[44:47], v[44:47], v[40:43], 0
	v_mfma_f32_16x16x32_bf16 v[48:51], v[48:51], v[40:43], 0
	v_mfma_f32_16x16x32_bf16 v[40:43], v[56:59], v[40:43], 0
	v_cvt_pk_bf16_f32 v56, v55, v60
	v_cvt_pk_bf16_f32 v57, v61, v62
	v_cvt_pk_bf16_f32 v58, v63, v66
	ds_read2_b64 v[60:63], v93 offset0:72 offset1:76
	v_cvt_pk_bf16_f32 v59, v68, v69
	s_waitcnt lgkmcnt(0)
	s_nop 0
	v_mfma_f32_16x16x32_bf16 v[36:39], v[60:63], v[56:59], v[36:39]
	ds_read2_b64 v[60:63], v124 offset0:232 offset1:236
	s_waitcnt lgkmcnt(0)
	v_mfma_f32_16x16x32_bf16 v[44:47], v[60:63], v[56:59], v[44:47]
	ds_read2_b64 v[60:63], v89 offset0:136 offset1:140
	s_waitcnt lgkmcnt(0)
	v_mfma_f32_16x16x32_bf16 v[48:51], v[60:63], v[56:59], v[48:51]
	ds_read2_b64 v[60:63], v91 offset0:40 offset1:44
	s_waitcnt lgkmcnt(0)
	v_mfma_f32_16x16x32_bf16 v[40:43], v[60:63], v[56:59], v[40:43]
	ds_read2_b64 v[60:63], v93 offset0:80 offset1:84
	v_cvt_pk_bf16_f32 v56, v70, v71
	v_cvt_pk_bf16_f32 v57, v72, v73
	v_cvt_pk_bf16_f32 v58, v74, v75
	v_cvt_pk_bf16_f32 v59, v114, v115
	s_waitcnt lgkmcnt(0)
	s_nop 0
	v_mfma_f32_16x16x32_bf16 v[36:39], v[60:63], v[56:59], v[36:39]
	ds_read2_b64 v[60:63], v124 offset0:240 offset1:244
	s_waitcnt lgkmcnt(0)
	v_mfma_f32_16x16x32_bf16 v[44:47], v[60:63], v[56:59], v[44:47]
	ds_read2_b64 v[60:63], v89 offset0:144 offset1:148
	s_waitcnt lgkmcnt(0)
	v_mfma_f32_16x16x32_bf16 v[48:51], v[60:63], v[56:59], v[48:51]
	ds_read2_b64 v[60:63], v91 offset0:48 offset1:52
	s_waitcnt lgkmcnt(0)
	v_mfma_f32_16x16x32_bf16 v[40:43], v[60:63], v[56:59], v[40:43]
	ds_read2_b64 v[60:63], v93 offset0:88 offset1:92
	v_cvt_pk_bf16_f32 v56, v116, v117
	v_cvt_pk_bf16_f32 v57, v118, v119
	v_cvt_pk_bf16_f32 v58, v120, v121
	v_cvt_pk_bf16_f32 v59, v122, v123
	s_waitcnt lgkmcnt(0)
	s_nop 0
	v_mfma_f32_16x16x32_bf16 v[36:39], v[60:63], v[56:59], v[36:39]
	ds_read2_b64 v[60:63], v124 offset0:248 offset1:252
	s_waitcnt lgkmcnt(0)
	v_mfma_f32_16x16x32_bf16 v[44:47], v[60:63], v[56:59], v[44:47]
	ds_read2_b64 v[60:63], v89 offset0:152 offset1:156
	s_waitcnt lgkmcnt(0)
	v_mfma_f32_16x16x32_bf16 v[60:63], v[60:63], v[56:59], v[48:51]
	s_nop 2
	ds_read2_b64 v[48:51], v91 offset0:56 offset1:60
	s_waitcnt lgkmcnt(0)
	v_mfma_f32_16x16x32_bf16 v[56:59], v[48:51], v[56:59], v[40:43]
	s_nop 2
	ds_read2_b64 v[40:43], v93 offset0:96 offset1:100
	v_cvt_pk_bf16_f32 v0, v125, v126
	v_cvt_pk_bf16_f32 v1, v127, v128
	v_mov_b32_e32 v3, v2
	v_add_u32_e32 v125, 0x7000, v171
	s_waitcnt lgkmcnt(0)
	v_mfma_f32_16x16x32_bf16 v[48:51], v[40:43], v[0:3], v[36:39]
	s_nop 2
	ds_read2_b64 v[36:39], v125 offset1:4
	s_waitcnt lgkmcnt(0)
	v_mfma_f32_16x16x32_bf16 v[44:47], v[36:39], v[0:3], v[44:47]
	ds_read2_b64 v[36:39], v89 offset0:160 offset1:164
	s_waitcnt lgkmcnt(0)
	v_mfma_f32_16x16x32_bf16 v[40:43], v[36:39], v[0:3], v[60:63]
	ds_read2_b64 v[36:39], v91 offset0:64 offset1:68
	s_waitcnt lgkmcnt(0)
	v_mfma_f32_16x16x32_bf16 v[36:39], v[36:39], v[0:3], v[56:59]
	v_or_b32_e32 v0, s70, v103
	s_movk_i32 s0, 0x810
	v_cmp_gt_i32_e32 vcc, s0, v0
	s_and_saveexec_b64 s[0:1], vcc
	v_sub_f32_e32 v0, v67, v52
	v_exp_f32_e32 v0, v0
	v_add_f32_e32 v1, v53, v54
	v_add_f32_e32 v3, v0, v1
	v_div_scale_f32 v52, s[4:5], v3, v3, 1.0
	v_rcp_f32_e32 v53, v52
	v_div_scale_f32 v54, vcc, 1.0, v3, 1.0
	v_lshl_add_u64 v[0:1], v[64:65], 0, v[112:113]
	v_fma_f32 v55, -v52, v53, 1.0
	v_fmac_f32_e32 v53, v55, v53
	v_mul_f32_e32 v55, v54, v53
	v_fma_f32 v56, -v52, v55, v54
	v_fmac_f32_e32 v55, v56, v53
	v_fma_f32 v52, -v52, v55, v54
	v_div_fmas_f32 v52, v52, v53, v55
	v_div_fixup_f32 v52, v52, v3, 1.0
	v_pk_mul_f32 v[48:49], v[52:53], v[48:49] op_sel_hi:[0,1]
	v_lshlrev_b32_e32 v54, 16, v110
	v_and_b32_e32 v55, 0xffff0000, v110
	v_pk_mul_f32 v[50:51], v[52:53], v[50:51] op_sel_hi:[0,1]
	v_pk_mul_f32 v[48:49], v[48:49], v[54:55]
	v_lshlrev_b32_e32 v54, 16, v111
	v_and_b32_e32 v55, 0xffff0000, v111
	v_pk_mul_f32 v[50:51], v[50:51], v[54:55]
	v_cvt_pk_bf16_f32 v48, v48, v49
	v_cvt_pk_bf16_f32 v49, v50, v51
	global_store_dwordx2 v[0:1], v[48:49], off
	v_pk_mul_f32 v[44:45], v[52:53], v[44:45] op_sel_hi:[0,1]
	v_lshlrev_b32_e32 v48, 16, v108
	v_and_b32_e32 v49, 0xffff0000, v108
	v_pk_mul_f32 v[46:47], v[52:53], v[46:47] op_sel_hi:[0,1]
	v_pk_mul_f32 v[44:45], v[44:45], v[48:49]
	v_lshlrev_b32_e32 v48, 16, v109
	v_and_b32_e32 v49, 0xffff0000, v109
	v_pk_mul_f32 v[46:47], v[46:47], v[48:49]
	v_cvt_pk_bf16_f32 v44, v44, v45
	v_cvt_pk_bf16_f32 v45, v46, v47
	global_store_dwordx2 v[0:1], v[44:45], off offset:32
	v_pk_mul_f32 v[40:41], v[52:53], v[40:41] op_sel_hi:[0,1]
	v_lshlrev_b32_e32 v44, 16, v106
	v_and_b32_e32 v45, 0xffff0000, v106
	v_pk_mul_f32 v[42:43], v[52:53], v[42:43] op_sel_hi:[0,1]
	v_pk_mul_f32 v[40:41], v[40:41], v[44:45]
	v_lshlrev_b32_e32 v44, 16, v107
	v_and_b32_e32 v45, 0xffff0000, v107
	v_pk_mul_f32 v[42:43], v[42:43], v[44:45]
	v_cvt_pk_bf16_f32 v40, v40, v41
	v_cvt_pk_bf16_f32 v41, v42, v43
	global_store_dwordx2 v[0:1], v[40:41], off offset:64
	v_pk_mul_f32 v[36:37], v[52:53], v[36:37] op_sel_hi:[0,1]
	v_lshlrev_b32_e32 v40, 16, v104
	v_and_b32_e32 v41, 0xffff0000, v104
	v_pk_mul_f32 v[38:39], v[52:53], v[38:39] op_sel_hi:[0,1]
	v_pk_mul_f32 v[36:37], v[36:37], v[40:41]
	v_lshlrev_b32_e32 v40, 16, v105
	v_and_b32_e32 v41, 0xffff0000, v105
	v_pk_mul_f32 v[38:39], v[38:39], v[40:41]
	v_cvt_pk_bf16_f32 v36, v36, v37
	v_cvt_pk_bf16_f32 v37, v38, v39
	global_store_dwordx2 v[0:1], v[36:37], off offset:96

.LBB0_564:
	v_sub_f32_e32 v3, v31, v66
	v_fmac_f32_e32 v3, 0x43130000, v102
	v_cndmask_b32_e64 v28, v214, v3, s[0:1]
	v_max_f32_e32 v3, v132, v132
	v_max_f32_e32 v3, v3, v28
	ds_bpermute_b32 v29, v173, v3
	ds_read2_b64 v[36:39], v124 offset0:224 offset1:228
	ds_read2_b64 v[40:43], v89 offset0:128 offset1:132
	ds_read2_b64 v[44:47], v91 offset0:32 offset1:36
	s_waitcnt lgkmcnt(3)
	v_max_f32_e32 v29, v29, v29
	v_max_f32_e32 v3, v3, v29
	ds_bpermute_b32 v29, v174, v3
	s_waitcnt lgkmcnt(0)
	v_max3_f32 v3, v3, v29, v67
	v_sub_f32_e32 v29, v127, v3
	v_exp_f32_e32 v29, v29
	v_sub_f32_e32 v30, v30, v3
	v_exp_f32_e32 v30, v30
	v_sub_f32_e32 v32, v128, v3
	v_exp_f32_e32 v32, v32
	v_sub_f32_e32 v33, v126, v3
	v_exp_f32_e32 v33, v33
	v_sub_f32_e32 v34, v104, v3
	v_add_f32_e32 v31, 0, v29
	v_exp_f32_e32 v48, v34
	v_sub_f32_e32 v34, v105, v3
	v_add_f32_e32 v31, v30, v31
	v_exp_f32_e32 v49, v34
	v_sub_f32_e32 v0, v0, v3
	v_add_f32_e32 v31, v32, v31
	v_exp_f32_e32 v50, v0
	v_sub_f32_e32 v1, v1, v3
	v_add_f32_e32 v31, v33, v31
	v_exp_f32_e32 v51, v1
	v_sub_f32_e32 v1, v68, v3
	v_add_f32_e32 v31, v48, v31
	v_exp_f32_e32 v52, v1
	v_sub_f32_e32 v1, v69, v3
	v_add_f32_e32 v31, v49, v31
	v_exp_f32_e32 v53, v1
	v_sub_f32_e32 v1, v70, v3
	v_add_f32_e32 v0, v50, v31
	v_exp_f32_e32 v54, v1
	v_sub_f32_e32 v1, v71, v3
	v_add_f32_e32 v0, v51, v0
	v_exp_f32_e32 v55, v1
	v_sub_f32_e32 v1, v72, v3
	v_add_f32_e32 v0, v52, v0
	v_exp_f32_e32 v56, v1
	v_sub_f32_e32 v1, v73, v3
	v_add_f32_e32 v0, v53, v0
	v_exp_f32_e32 v57, v1
	v_sub_f32_e32 v1, v74, v3
	v_add_f32_e32 v0, v54, v0
	v_exp_f32_e32 v58, v1
	v_sub_f32_e32 v1, v75, v3
	v_add_f32_e32 v0, v55, v0
	v_exp_f32_e32 v59, v1
	v_sub_f32_e32 v1, v106, v3
	v_add_f32_e32 v0, v56, v0
	v_exp_f32_e32 v60, v1
	v_sub_f32_e32 v1, v107, v3
	v_add_f32_e32 v0, v57, v0
	v_exp_f32_e32 v61, v1
	v_sub_f32_e32 v1, v110, v3
	v_add_f32_e32 v0, v58, v0
	v_exp_f32_e32 v62, v1
	v_sub_f32_e32 v1, v111, v3
	v_add_f32_e32 v0, v59, v0
	v_exp_f32_e32 v63, v1
	v_sub_f32_e32 v1, v112, v3
	v_add_f32_e32 v0, v60, v0
	v_exp_f32_e32 v66, v1
	v_sub_f32_e32 v1, v113, v3
	v_add_f32_e32 v0, v61, v0
	v_exp_f32_e32 v68, v1
	v_sub_f32_e32 v1, v114, v3
	v_add_f32_e32 v0, v62, v0
	v_exp_f32_e32 v69, v1
	v_sub_f32_e32 v1, v115, v3
	v_add_f32_e32 v0, v63, v0
	v_exp_f32_e32 v70, v1
	v_sub_f32_e32 v1, v116, v3
	v_add_f32_e32 v0, v66, v0
	v_exp_f32_e32 v71, v1
	v_sub_f32_e32 v1, v117, v3
	v_add_f32_e32 v0, v68, v0
	v_exp_f32_e32 v72, v1
	v_sub_f32_e32 v1, v118, v3
	v_add_f32_e32 v0, v69, v0
	v_exp_f32_e32 v73, v1
	v_sub_f32_e32 v1, v119, v3
	v_add_f32_e32 v0, v70, v0
	v_exp_f32_e32 v74, v1
	v_sub_f32_e32 v1, v120, v3
	v_add_f32_e32 v0, v71, v0
	v_exp_f32_e32 v75, v1
	v_sub_f32_e32 v1, v121, v3
	v_add_f32_e32 v0, v72, v0
	v_exp_f32_e32 v102, v1
	v_sub_f32_e32 v1, v122, v3
	v_add_f32_e32 v0, v73, v0
	v_exp_f32_e32 v104, v1
	v_sub_f32_e32 v1, v123, v3
	v_add_f32_e32 v0, v74, v0
	v_exp_f32_e32 v105, v1
	v_sub_f32_e32 v1, v131, v3
	v_add_f32_e32 v0, v75, v0
	v_exp_f32_e32 v106, v1
	v_sub_f32_e32 v1, v129, v3
	v_add_f32_e32 v0, v102, v0
	v_exp_f32_e32 v107, v1
	v_sub_f32_e32 v1, v130, v3
	v_add_f32_e32 v0, v104, v0
	v_exp_f32_e32 v108, v1
	v_sub_f32_e32 v1, v28, v3
	v_add_f32_e32 v0, v105, v0
	v_exp_f32_e32 v109, v1
	v_add_f32_e32 v0, v106, v0
	v_add_f32_e32 v0, v107, v0
	v_add_f32_e32 v0, v108, v0
	v_cvt_pk_bf16_f32 v31, v32, v33
	ds_read2_b64 v[32:35], v93 offset0:64 offset1:68
	v_add_f32_e32 v0, v109, v0
	ds_bpermute_b32 v1, v173, v0
	v_cvt_pk_bf16_f32 v30, v29, v30
	v_mov_b32_e32 v28, v2
	v_mov_b32_e32 v29, v2
	s_waitcnt lgkmcnt(0)
	v_add_f32_e32 v0, v0, v1
	ds_bpermute_b32 v1, v174, v0
	v_mfma_f32_16x16x32_bf16 v[32:35], v[32:35], v[28:31], 0
	v_mfma_f32_16x16x32_bf16 v[36:39], v[36:39], v[28:31], 0
	v_mfma_f32_16x16x32_bf16 v[40:43], v[40:43], v[28:31], 0
	v_mfma_f32_16x16x32_bf16 v[28:31], v[44:47], v[28:31], 0
	v_cvt_pk_bf16_f32 v44, v48, v49
	v_cvt_pk_bf16_f32 v45, v50, v51
	ds_read2_b64 v[48:51], v93 offset0:72 offset1:76
	v_cvt_pk_bf16_f32 v46, v52, v53
	v_cvt_pk_bf16_f32 v47, v54, v55
	s_waitcnt lgkmcnt(0)
	s_nop 0
	v_mfma_f32_16x16x32_bf16 v[32:35], v[48:51], v[44:47], v[32:35]
	ds_read2_b64 v[48:51], v124 offset0:232 offset1:236
	s_waitcnt lgkmcnt(0)
	v_mfma_f32_16x16x32_bf16 v[36:39], v[48:51], v[44:47], v[36:39]
	ds_read2_b64 v[48:51], v89 offset0:136 offset1:140
	s_waitcnt lgkmcnt(0)
	v_mfma_f32_16x16x32_bf16 v[40:43], v[48:51], v[44:47], v[40:43]
	ds_read2_b64 v[48:51], v91 offset0:40 offset1:44
	s_waitcnt lgkmcnt(0)
	v_mfma_f32_16x16x32_bf16 v[28:31], v[48:51], v[44:47], v[28:31]
	ds_read2_b64 v[48:51], v93 offset0:80 offset1:84
	v_cvt_pk_bf16_f32 v44, v56, v57
	v_cvt_pk_bf16_f32 v45, v58, v59
	v_cvt_pk_bf16_f32 v46, v60, v61
	v_cvt_pk_bf16_f32 v47, v62, v63
	s_waitcnt lgkmcnt(0)
	s_nop 0
	v_mfma_f32_16x16x32_bf16 v[32:35], v[48:51], v[44:47], v[32:35]
	ds_read2_b64 v[48:51], v124 offset0:240 offset1:244
	s_waitcnt lgkmcnt(0)
	v_mfma_f32_16x16x32_bf16 v[36:39], v[48:51], v[44:47], v[36:39]
	ds_read2_b64 v[48:51], v89 offset0:144 offset1:148
	s_waitcnt lgkmcnt(0)
	v_mfma_f32_16x16x32_bf16 v[40:43], v[48:51], v[44:47], v[40:43]
	ds_read2_b64 v[48:51], v91 offset0:48 offset1:52
	s_waitcnt lgkmcnt(0)
	v_mfma_f32_16x16x32_bf16 v[28:31], v[48:51], v[44:47], v[28:31]
	ds_read2_b64 v[48:51], v93 offset0:88 offset1:92
	v_cvt_pk_bf16_f32 v44, v66, v68
	v_cvt_pk_bf16_f32 v45, v69, v70
	v_cvt_pk_bf16_f32 v46, v71, v72
	v_cvt_pk_bf16_f32 v47, v73, v74
	s_waitcnt lgkmcnt(0)
	s_nop 0
	v_mfma_f32_16x16x32_bf16 v[32:35], v[48:51], v[44:47], v[32:35]
	ds_read2_b64 v[48:51], v124 offset0:248 offset1:252
	s_waitcnt lgkmcnt(0)
	v_mfma_f32_16x16x32_bf16 v[36:39], v[48:51], v[44:47], v[36:39]
	ds_read2_b64 v[48:51], v89 offset0:152 offset1:156
	s_waitcnt lgkmcnt(0)
	v_mfma_f32_16x16x32_bf16 v[48:51], v[48:51], v[44:47], v[40:43]
	s_nop 2
	ds_read2_b64 v[40:43], v91 offset0:56 offset1:60
	s_waitcnt lgkmcnt(0)
	v_mfma_f32_16x16x32_bf16 v[28:31], v[40:43], v[44:47], v[28:31]
	ds_read2_b64 v[40:43], v93 offset0:96 offset1:100
	v_cvt_pk_bf16_f32 v44, v75, v102
	v_cvt_pk_bf16_f32 v45, v104, v105
	v_cvt_pk_bf16_f32 v46, v106, v107
	v_cvt_pk_bf16_f32 v47, v108, v109
	s_waitcnt lgkmcnt(0)
	s_nop 0
	v_mfma_f32_16x16x32_bf16 v[40:43], v[40:43], v[44:47], v[32:35]
	s_nop 2
	ds_read2_b64 v[32:35], v125 offset1:4
	s_waitcnt lgkmcnt(0)
	v_mfma_f32_16x16x32_bf16 v[36:39], v[32:35], v[44:47], v[36:39]
	ds_read2_b64 v[32:35], v89 offset0:160 offset1:164
	s_waitcnt lgkmcnt(0)
	v_mfma_f32_16x16x32_bf16 v[32:35], v[32:35], v[44:47], v[48:51]
	s_nop 2
	ds_read2_b64 v[48:51], v91 offset0:64 offset1:68
	s_waitcnt lgkmcnt(0)
	v_mfma_f32_16x16x32_bf16 v[28:31], v[48:51], v[44:47], v[28:31]
	v_or_b32_e32 v44, s70, v153
	s_movk_i32 s0, 0x810
	v_cmp_gt_i32_e32 vcc, s0, v44
	s_and_saveexec_b64 s[0:1], vcc
	v_sub_f32_e32 v3, v67, v3
	v_exp_f32_e32 v3, v3
	v_add_f32_e32 v0, v0, v1
	v_and_b32_e32 v47, 0xffff0000, v100
	v_add_f32_e32 v0, v3, v0
	v_div_scale_f32 v1, s[4:5], v0, v0, 1.0
	v_rcp_f32_e32 v3, v1
	s_nop 0
	v_fma_f32 v44, -v1, v3, 1.0
	v_fmac_f32_e32 v3, v44, v3
	v_div_scale_f32 v44, vcc, 1.0, v0, 1.0
	v_mul_f32_e32 v45, v44, v3
	v_fma_f32 v46, -v1, v45, v44
	v_fmac_f32_e32 v45, v46, v3
	v_fma_f32 v1, -v1, v45, v44
	v_div_fmas_f32 v1, v1, v3, v45
	v_div_fixup_f32 v0, v1, v0, 1.0
	v_add_u32_e32 v44, s60, v153
	v_pk_mul_f32 v[40:41], v[0:1], v[40:41] op_sel_hi:[0,1]
	v_lshlrev_b32_e32 v46, 16, v100
	v_ashrrev_i32_e32 v45, 31, v44
	v_pk_mul_f32 v[42:43], v[0:1], v[42:43] op_sel_hi:[0,1]
	v_pk_mul_f32 v[40:41], v[40:41], v[46:47]
	v_lshlrev_b32_e32 v46, 16, v101
	v_and_b32_e32 v47, 0xffff0000, v101
	v_lshlrev_b64 v[44:45], 13, v[44:45]
	v_pk_mul_f32 v[42:43], v[42:43], v[46:47]
	v_lshl_add_u64 v[44:45], v[64:65], 0, v[44:45]
	v_cvt_pk_bf16_f32 v40, v40, v41
	v_cvt_pk_bf16_f32 v41, v42, v43
	global_store_dwordx2 v[44:45], v[40:41], off
	v_pk_mul_f32 v[36:37], v[0:1], v[36:37] op_sel_hi:[0,1]
	v_lshlrev_b32_e32 v40, 16, v98
	v_and_b32_e32 v41, 0xffff0000, v98
	v_pk_mul_f32 v[38:39], v[0:1], v[38:39] op_sel_hi:[0,1]
	v_pk_mul_f32 v[36:37], v[36:37], v[40:41]
	v_lshlrev_b32_e32 v40, 16, v99
	v_and_b32_e32 v41, 0xffff0000, v99
	v_pk_mul_f32 v[38:39], v[38:39], v[40:41]
	v_cvt_pk_bf16_f32 v36, v36, v37
	v_cvt_pk_bf16_f32 v37, v38, v39
	global_store_dwordx2 v[44:45], v[36:37], off offset:32
	v_pk_mul_f32 v[34:35], v[0:1], v[34:35] op_sel_hi:[0,1]
	v_pk_mul_f32 v[32:33], v[0:1], v[32:33] op_sel_hi:[0,1]
	v_lshlrev_b32_e32 v36, 16, v96
	v_and_b32_e32 v37, 0xffff0000, v96
	v_pk_mul_f32 v[30:31], v[0:1], v[30:31] op_sel_hi:[0,1]
	v_pk_mul_f32 v[0:1], v[0:1], v[28:29] op_sel_hi:[0,1]
	v_lshlrev_b32_e32 v28, 16, v94
	v_and_b32_e32 v29, 0xffff0000, v94
	v_pk_mul_f32 v[32:33], v[32:33], v[36:37]
	v_lshlrev_b32_e32 v36, 16, v97
	v_and_b32_e32 v37, 0xffff0000, v97
	v_pk_mul_f32 v[0:1], v[0:1], v[28:29]
	v_lshlrev_b32_e32 v28, 16, v95
	v_and_b32_e32 v29, 0xffff0000, v95
	v_pk_mul_f32 v[34:35], v[34:35], v[36:37]
	v_pk_mul_f32 v[28:29], v[30:31], v[28:29]
	v_cvt_pk_bf16_f32 v32, v32, v33
	v_cvt_pk_bf16_f32 v33, v34, v35
	v_cvt_pk_bf16_f32 v0, v0, v1
	v_cvt_pk_bf16_f32 v1, v28, v29
	global_store_dwordx2 v[44:45], v[32:33], off offset:64
	global_store_dwordx2 v[44:45], v[0:1], off offset:96
	s_branch .LBB0_547
.LBB0_566:
	s_waitcnt vmcnt(0)
	v_readlane_b32 s0, v252, 36
	v_readlane_b32 s1, v252, 37
	v_readlane_b32 s34, v254, 48
	s_andn2_b64 vcc, exec, s[0:1]
	s_mov_b32 s2, s51
	v_readlane_b32 s35, v254, 49
	v_readlane_b32 s70, v254, 54
	v_readlane_b32 s60, v254, 50
	v_readlane_b32 s36, v254, 51
	v_readlane_b32 s44, v254, 52
	v_readlane_b32 s4, v254, 57
	v_readlane_b32 s45, v254, 53
	v_readlane_b32 s5, v254, 58
	s_cbranch_vccnz .LBB0_589
	v_and_b32_e32 v1, 64, v208
	v_xor_b32_e32 v0, 16, v208
	v_add_u32_e32 v1, 64, v1
	v_cmp_lt_i32_e32 vcc, v0, v1
	s_movk_i32 s0, 0x500
	v_cmp_gt_i32_e64 s[38:39], s0, v76
	v_cndmask_b32_e32 v0, v208, v0, vcc
	v_lshlrev_b32_e32 v25, 2, v0
	v_xor_b32_e32 v0, 32, v208
	v_readlane_b32 s0, v255, 1
	v_cmp_lt_i32_e32 vcc, v0, v1
	s_lshl_b32 s16, s0, 6
	s_movk_i32 s0, 0x81
	v_cndmask_b32_e32 v0, v208, v0, vcc
	v_lshlrev_b32_e32 v34, 2, v0
	s_movk_i32 s3, 0x80
	v_subrev_co_u32_e64 v0, s[42:43], s0, v137
	v_add_u32_e32 v1, -2, v137
	v_cmp_gt_u32_e64 s[4:5], s3, v0
	v_add_u32_e32 v0, 0xffffff7e, v137
	v_readlane_b32 s1, v255, 2
	v_cmp_gt_u32_e64 s[44:45], s3, v1
	v_add_u32_e32 v1, -3, v137
	v_cmp_gt_u32_e64 s[50:51], s3, v0
	v_add_u32_e32 v0, 0xffffff7d, v137
	v_and_b32_e32 v4, 7, v76
	v_readlane_b32 s6, v252, 25
	v_cmp_gt_u32_e64 s[0:1], s3, v1
	v_cmp_gt_u32_e64 s[52:53], s3, v0
	v_lshlrev_b32_e32 v0, 4, v4
	v_mov_b32_e32 v1, v2
	v_readlane_b32 s7, v252, 26
	v_readlane_b32 s76, v251, 55
	v_and_b32_e32 v35, 63, v76
	v_lshl_add_u64 v[22:23], s[6:7], 0, v[0:1]
	v_add_u32_e32 v24, 0, v0
	v_lshlrev_b32_e32 v0, 5, v4
	v_readlane_b32 s82, v251, 61
	v_readlane_b32 s83, v251, 62
	v_mov_b32_e32 v81, v2
	s_waitcnt lgkmcnt(0)
	v_lshl_add_u32 v3, v136, 3, 0
	v_cmp_gt_u32_e64 s[40:41], s3, v137
	s_movk_i32 s3, 0x150
	v_readlane_b32 s84, v251, 63
	v_readlane_b32 s85, v252, 0
	v_lshl_add_u64 v[26:27], s[82:83], 0, v[0:1]
	v_lshlrev_b32_e32 v0, 2, v35
	v_lshl_add_u64 v[20:21], s[64:65], 0, v[80:81]
	v_cvt_f32_ubyte0_e32 v161, v137
	v_cmp_gt_u32_e64 s[54:55], 8, v103
	v_mad_u32_u24 v36, v35, s3, 0
	v_or_b32_e32 v37, 0x2040, v103
	v_lshl_add_u64 v[28:29], s[84:85], 0, v[0:1]
	v_add_u32_e32 v38, v79, v80
	v_add_u32_e32 v39, v3, v77
	v_readlane_b32 s17, v252, 35
	v_readlane_b32 s77, v251, 56
	v_readlane_b32 s78, v251, 57
	v_readlane_b32 s79, v251, 58
	v_readlane_b32 s80, v251, 59
	v_readlane_b32 s81, v251, 60
	v_readlane_b32 s86, v252, 1
	v_readlane_b32 s87, v252, 2
	v_readlane_b32 s88, v252, 3
	v_readlane_b32 s89, v252, 4
	v_readlane_b32 s90, v252, 5
	v_readlane_b32 s91, v252, 6
	s_branch .LBB0_569
